# T21 widened epilogue stores: dwordx2 pairs -> permlane32_swap + dwordx4 in 8 attention epilogues; vmcnt recount; drop redundant waits in NSA2 second sub-block
# speedup vs baseline: 1.0193x; 1.0193x over previous
.LBB0_517:
	s_or_b64 exec, exec, s[4:5]
	s_waitcnt lgkmcnt(0)
	v_mul_f32_e32 v25, v4, v47
	v_mul_f32_e32 v27, v5, v47
	v_mul_f32_e32 v24, v1, v47
	v_mul_f32_e32 v26, v2, v47
	v_mul_f32_e32 v31, v7, v47
	v_cndmask_b32_e64 v4, 0, v27, s[2:3]
	v_fma_f32 v1, v1, v47, v25
	v_fma_f32 v2, v2, v47, v27
	ds_bpermute_b32 v4, v97, v4
	v_add_f32_e32 v1, v1, v2
	v_cndmask_b32_e64 v2, v27, v31, s[2:3]
	ds_bpermute_b32 v2, v97, v2
	v_mul_f32_e32 v29, v6, v47
	v_mul_f32_e32 v28, v0, v47
	v_mul_f32_e32 v30, v3, v47
	v_fma_f32 v0, v0, v47, v29
	v_fma_f32 v3, v3, v47, v31
	v_mul_f32_e32 v81, v8, v47
	v_mul_f32_e32 v82, v9, v47
	v_mul_f32_e32 v83, v10, v47
	v_mul_f32_e32 v84, v11, v47
	s_waitcnt lgkmcnt(1)
	v_add_f32_e32 v1, v1, v4
	ds_read2_b32 v[4:5], v96 offset1:2
	ds_read2_b32 v[6:7], v96 offset0:4 offset1:6
	ds_read2_b32 v[8:9], v96 offset0:8 offset1:10
	ds_read2_b32 v[10:11], v96 offset0:12 offset1:14
	v_add_f32_e32 v0, v0, v3
	s_waitcnt lgkmcnt(4)
	v_add_f32_e32 v0, v0, v2
	s_waitcnt lgkmcnt(3)
	v_add_f32_e32 v1, v4, v1
	v_add_f32_e32 v0, v5, v0
	v_cndmask_b32_e64 v2, v31, v82, s[2:3]
	ds_bpermute_b32 v2, v97, v2
	ds_write2_b32 v96, v1, v0 offset1:2
	v_fma_f32 v0, v72, v47, v81
	v_fma_f32 v1, v73, v47, v82
	v_add_f32_e32 v0, v0, v1
	v_cndmask_b32_e64 v1, v82, v84, s[2:3]
	ds_bpermute_b32 v1, v97, v1
	s_waitcnt lgkmcnt(2)
	v_add_f32_e32 v0, v0, v2
	v_fma_f32 v2, v74, v47, v83
	v_fma_f32 v3, v75, v47, v84
	v_add_f32_e32 v2, v2, v3
	v_mul_f32_e32 v86, v13, v47
	s_waitcnt lgkmcnt(0)
	v_add_f32_e32 v1, v2, v1
	v_mul_f32_e32 v85, v12, v47
	v_add_f32_e32 v0, v6, v0
	v_add_f32_e32 v1, v7, v1
	v_cndmask_b32_e64 v2, v84, v86, s[2:3]
	v_mul_f32_e32 v164, v15, v47
	ds_bpermute_b32 v2, v97, v2
	ds_write2_b32 v96, v0, v1 offset0:4 offset1:6
	v_fma_f32 v0, v54, v47, v85
	v_fma_f32 v1, v52, v47, v86
	v_add_f32_e32 v0, v0, v1
	v_cndmask_b32_e64 v1, v86, v164, s[2:3]
	ds_bpermute_b32 v1, v97, v1
	v_mul_f32_e32 v87, v14, v47
	s_waitcnt lgkmcnt(2)
	v_add_f32_e32 v0, v0, v2
	v_fma_f32 v2, v53, v47, v87
	v_fma_f32 v3, v55, v47, v164
	v_add_f32_e32 v2, v2, v3
	v_mul_f32_e32 v166, v61, v47
	s_waitcnt lgkmcnt(0)
	v_add_f32_e32 v1, v2, v1
	v_mul_f32_e32 v165, v60, v47
	v_add_f32_e32 v0, v8, v0
	v_add_f32_e32 v1, v9, v1
	v_cndmask_b32_e64 v2, v164, v166, s[2:3]
	v_mul_f32_e32 v57, v57, v47
	ds_bpermute_b32 v2, v97, v2
	ds_write2_b32 v96, v0, v1 offset0:8 offset1:10
	v_fma_f32 v0, v48, v47, v165
	v_fma_f32 v1, v49, v47, v166
	v_add_f32_e32 v0, v0, v1
	v_cndmask_b32_e64 v1, v166, v57, s[2:3]
	ds_bpermute_b32 v1, v97, v1
	v_mul_f32_e32 v167, v58, v47
	s_waitcnt lgkmcnt(2)
	v_add_f32_e32 v0, v0, v2
	v_fma_f32 v2, v50, v47, v167
	v_fma_f32 v3, v51, v47, v57
	v_add_f32_e32 v2, v2, v3
	s_waitcnt lgkmcnt(0)
	v_add_f32_e32 v1, v2, v1
	v_mul_f32_e32 v62, v62, v47
	v_add_f32_e32 v0, v10, v0
	v_add_f32_e32 v1, v11, v1
	ds_write2_b32 v96, v0, v1 offset0:12 offset1:14
	v_cndmask_b32_e64 v0, v57, v62, s[2:3]
	ds_bpermute_b32 v2, v97, v0
	v_mul_f32_e32 v168, v59, v47
	v_fma_f32 v3, v38, v47, v168
	v_fma_f32 v4, v36, v47, v62
	v_mul_f32_e32 v169, v76, v47
	ds_read2_b32 v[0:1], v96 offset0:16 offset1:18
	v_add_f32_e32 v3, v3, v4
	s_waitcnt lgkmcnt(1)
	v_add_f32_e32 v2, v3, v2
	v_cndmask_b32_e64 v3, v62, v169, s[2:3]
	ds_bpermute_b32 v3, v97, v3
	v_mul_f32_e32 v63, v63, v47
	s_waitcnt lgkmcnt(1)
	v_add_f32_e32 v0, v0, v2
	v_fma_f32 v2, v39, v47, v63
	v_fma_f32 v4, v56, v47, v169
	v_add_f32_e32 v2, v2, v4
	s_waitcnt lgkmcnt(0)
	v_add_f32_e32 v2, v2, v3
	v_mul_f32_e32 v171, v78, v47
	v_add_f32_e32 v1, v1, v2
	ds_write2_b32 v96, v0, v1 offset0:16 offset1:18
	v_cndmask_b32_e64 v0, v169, v171, s[2:3]
	ds_bpermute_b32 v2, v97, v0
	v_mul_f32_e32 v170, v77, v47
	v_fma_f32 v3, v32, v47, v170
	v_fma_f32 v4, v34, v47, v171
	v_mul_f32_e32 v80, v80, v47
	ds_read2_b32 v[0:1], v96 offset0:20 offset1:22
	v_add_f32_e32 v3, v3, v4
	s_waitcnt lgkmcnt(1)
	v_add_f32_e32 v2, v3, v2
	v_cndmask_b32_e64 v3, v171, v80, s[2:3]
	ds_bpermute_b32 v3, v97, v3
	v_mul_f32_e32 v172, v79, v47
	s_waitcnt lgkmcnt(1)
	v_add_f32_e32 v0, v0, v2
	v_fma_f32 v2, v42, v47, v172
	v_fma_f32 v4, v43, v47, v80
	v_add_f32_e32 v2, v2, v4
	s_waitcnt lgkmcnt(0)
	v_add_f32_e32 v2, v2, v3
	v_mul_f32_e32 v174, v20, v47
	v_add_f32_e32 v1, v1, v2
	ds_write2_b32 v96, v0, v1 offset0:20 offset1:22
	v_cndmask_b32_e64 v0, v80, v174, s[2:3]
	ds_bpermute_b32 v2, v97, v0
	v_mul_f32_e32 v173, v22, v47
	v_fma_f32 v3, v33, v47, v173
	v_fma_f32 v4, v35, v47, v174
	v_mul_f32_e32 v176, v17, v47
	ds_read2_b32 v[0:1], v96 offset0:24 offset1:26
	v_add_f32_e32 v3, v3, v4
	s_waitcnt lgkmcnt(1)
	v_add_f32_e32 v2, v3, v2
	v_cndmask_b32_e64 v3, v174, v176, s[2:3]
	ds_bpermute_b32 v3, v97, v3
	v_mul_f32_e32 v175, v16, v47
	s_waitcnt lgkmcnt(1)
	v_add_f32_e32 v0, v0, v2
	v_fma_f32 v2, v40, v47, v175
	v_fma_f32 v4, v44, v47, v176
	v_add_f32_e32 v2, v2, v4
	s_waitcnt lgkmcnt(0)
	v_add_f32_e32 v2, v2, v3
	v_mul_f32_e32 v178, v19, v47
	v_add_f32_e32 v1, v1, v2
	ds_write2_b32 v96, v0, v1 offset0:24 offset1:26
	v_cndmask_b32_e64 v0, v176, v178, s[2:3]
	ds_bpermute_b32 v2, v97, v0
	v_mul_f32_e32 v177, v18, v47
	v_fma_f32 v3, v37, v47, v177
	v_fma_f32 v4, v41, v47, v178
	v_mul_f32_e32 v180, v21, v47
	ds_read2_b32 v[0:1], v96 offset0:28 offset1:30
	v_add_f32_e32 v3, v3, v4
	s_waitcnt lgkmcnt(1)
	v_add_f32_e32 v2, v3, v2
	v_cndmask_b32_e64 v3, v178, v180, s[2:3]
	ds_bpermute_b32 v3, v97, v3
	v_mul_f32_e32 v179, v23, v47
	s_waitcnt lgkmcnt(1)
	v_add_f32_e32 v0, v0, v2
	v_fma_f32 v2, v45, v47, v179
	v_fma_f32 v4, v46, v47, v180
	v_add_f32_e32 v2, v2, v4
	s_waitcnt lgkmcnt(0)
	v_add_f32_e32 v2, v2, v3
	v_add_f32_e32 v1, v1, v2
	ds_write2_b32 v96, v0, v1 offset0:28 offset1:30
	v_cvt_pk_bf16_f32 v16, v24, v25
	v_cvt_pk_bf16_f32 v17, v26, v27
	v_cvt_pk_bf16_f32 v18, v28, v29
	v_cvt_pk_bf16_f32 v19, v30, v31
	ds_read_b64_tr_b16 v[0:1], v163 offset:18432
	ds_read_b64_tr_b16 v[2:3], v163 offset:19968
	ds_read_b64_tr_b16 v[22:23], v163 offset:20032
	ds_read_b64_tr_b16 v[20:21], v163 offset:18496
	s_waitcnt lgkmcnt(2)
	v_mfma_f32_32x32x16_bf16 v[0:15], v[0:3], v[16:19], 0
	v_mul_f32_e32 v58, v72, v47
	v_mul_f32_e32 v59, v73, v47
	v_mul_f32_e32 v60, v74, v47
	v_mul_f32_e32 v61, v75, v47
	v_cvt_pk_bf16_f32 v58, v58, v81
	v_cvt_pk_bf16_f32 v59, v59, v82
	v_cvt_pk_bf16_f32 v60, v60, v83
	s_waitcnt lgkmcnt(0)
	v_mfma_f32_32x32x16_bf16 v[16:31], v[20:23], v[16:19], 0
	v_cvt_pk_bf16_f32 v61, v61, v84
	ds_read_b64_tr_b16 v[72:73], v163 offset:21504
	ds_read_b64_tr_b16 v[74:75], v163 offset:23040
	ds_read_b64_tr_b16 v[78:79], v163 offset:23104
	ds_read_b64_tr_b16 v[76:77], v163 offset:21568
	v_mul_f32_e32 v54, v54, v47
	v_mul_f32_e32 v55, v55, v47
	v_mul_f32_e32 v48, v48, v47
	v_mul_f32_e32 v49, v49, v47
	v_mul_f32_e32 v50, v50, v47
	s_waitcnt lgkmcnt(2)
	v_mfma_f32_32x32x16_bf16 v[0:15], v[72:75], v[58:61], v[0:15]
	v_mul_f32_e32 v72, v52, v47
	v_mul_f32_e32 v73, v53, v47
	v_cvt_pk_bf16_f32 v52, v54, v85
	v_cvt_pk_bf16_f32 v53, v72, v86
	v_cvt_pk_bf16_f32 v54, v73, v87
	v_cvt_pk_bf16_f32 v55, v55, v164
	v_mul_f32_e32 v51, v51, v47
	s_waitcnt lgkmcnt(0)
	v_mfma_f32_32x32x16_bf16 v[16:31], v[76:79], v[58:61], v[16:31]
	ds_read_b64_tr_b16 v[58:59], v163 offset:24576
	ds_read_b64_tr_b16 v[60:61], v163 offset:26112
	ds_read_b64_tr_b16 v[74:75], v163 offset:26176
	ds_read_b64_tr_b16 v[72:73], v163 offset:24640
	v_cvt_pk_bf16_f32 v48, v48, v165
	v_cvt_pk_bf16_f32 v49, v49, v166
	v_cvt_pk_bf16_f32 v50, v50, v167
	v_cvt_pk_bf16_f32 v51, v51, v57
	v_mul_f32_e32 v38, v38, v47
	v_mul_f32_e32 v36, v36, v47
	s_waitcnt lgkmcnt(2)
	v_mfma_f32_32x32x16_bf16 v[0:15], v[58:61], v[52:55], v[0:15]
	v_mul_f32_e32 v39, v39, v47
	v_mul_f32_e32 v32, v32, v47
	v_mul_f32_e32 v34, v34, v47
	v_mul_f32_e32 v41, v41, v47
	s_addk_i32 s20, 0x210
	v_lshl_add_u64 v[68:69], v[68:69], 0, s[14:15]
	s_cmpk_eq_i32 s20, 0x18c0
	s_waitcnt lgkmcnt(0)
	v_mfma_f32_32x32x16_bf16 v[16:31], v[72:75], v[52:55], v[16:31]
	ds_read_b64_tr_b16 v[52:53], v163 offset:27648
	ds_read_b64_tr_b16 v[54:55], v163 offset:29184
	ds_read_b64_tr_b16 v[60:61], v163 offset:29248
	ds_read_b64_tr_b16 v[58:59], v163 offset:27712
	s_waitcnt lgkmcnt(2)
	v_mfma_f32_32x32x16_bf16 v[0:15], v[52:55], v[48:51], v[0:15]
	v_mul_f32_e32 v52, v56, v47
	s_waitcnt lgkmcnt(0)
	v_mfma_f32_32x32x16_bf16 v[16:31], v[58:61], v[48:51], v[16:31]
	v_cvt_pk_bf16_f32 v48, v38, v168
	v_cvt_pk_bf16_f32 v49, v36, v62
	v_cvt_pk_bf16_f32 v50, v39, v63
	v_cvt_pk_bf16_f32 v51, v52, v169
	ds_read_b64_tr_b16 v[52:53], v163 offset:30720
	ds_read_b64_tr_b16 v[54:55], v163 offset:32256
	ds_read_b64_tr_b16 v[58:59], v163 offset:32320
	ds_read_b64_tr_b16 v[56:57], v163 offset:30784
	v_mul_f32_e32 v36, v42, v47
	v_mul_f32_e32 v38, v43, v47
	s_waitcnt lgkmcnt(2)
	v_mfma_f32_32x32x16_bf16 v[0:15], v[52:55], v[48:51], v[0:15]
	v_mul_f32_e32 v42, v45, v47
	v_mul_f32_e32 v43, v46, v47
	s_waitcnt lgkmcnt(0)
	v_mfma_f32_32x32x16_bf16 v[16:31], v[56:59], v[48:51], v[16:31]
	v_cvt_pk_bf16_f32 v48, v32, v170
	v_cvt_pk_bf16_f32 v49, v34, v171
	v_cvt_pk_bf16_f32 v50, v36, v172
	v_cvt_pk_bf16_f32 v51, v38, v80
	ds_read_b64_tr_b16 v[52:53], v163 offset:33792
	ds_read_b64_tr_b16 v[54:55], v163 offset:35328
	ds_read_b64_tr_b16 v[58:59], v163 offset:35392
	ds_read_b64_tr_b16 v[56:57], v163 offset:33856
	v_mul_f32_e32 v32, v33, v47
	v_mul_f32_e32 v33, v35, v47
	v_mul_f32_e32 v34, v40, v47
	v_mul_f32_e32 v35, v44, v47
	v_mul_f32_e32 v40, v37, v47
	s_waitcnt lgkmcnt(2)
	v_mfma_f32_32x32x16_bf16 v[0:15], v[52:55], v[48:51], v[0:15]
	v_cvt_pk_bf16_f32 v32, v32, v173
	v_cvt_pk_bf16_f32 v33, v33, v174
	v_cvt_pk_bf16_f32 v34, v34, v175
	v_cvt_pk_bf16_f32 v35, v35, v176
	s_waitcnt lgkmcnt(0)
	v_mfma_f32_32x32x16_bf16 v[16:31], v[56:59], v[48:51], v[16:31]
	ds_read_b64_tr_b16 v[48:49], v163 offset:36864
	ds_read_b64_tr_b16 v[50:51], v163 offset:38400
	ds_read_b64_tr_b16 v[38:39], v163 offset:38464
	ds_read_b64_tr_b16 v[36:37], v163 offset:36928
	v_cvt_pk_bf16_f32 v40, v40, v177
	v_cvt_pk_bf16_f32 v41, v41, v178
	v_cvt_pk_bf16_f32 v42, v42, v179
	v_cvt_pk_bf16_f32 v43, v43, v180
	s_nop 0
	s_waitcnt lgkmcnt(2)
	v_mfma_f32_32x32x16_bf16 v[0:15], v[48:51], v[32:35], v[0:15]
	v_lshl_add_u64 v[66:67], v[66:67], 0, 6
	s_waitcnt lgkmcnt(0)
	v_mfma_f32_32x32x16_bf16 v[16:31], v[36:39], v[32:35], v[16:31]
	ds_read_b64_tr_b16 v[32:33], v163 offset:39936
	ds_read_b64_tr_b16 v[34:35], v163 offset:41472
	ds_read_b64_tr_b16 v[38:39], v163 offset:41536
	ds_read_b64_tr_b16 v[36:37], v163 offset:40000
	s_waitcnt lgkmcnt(2)
	v_mfma_f32_32x32x16_bf16 v[0:15], v[32:35], v[40:43], v[0:15]
	s_nop 0
	v_lshlrev_b32_e32 v32, 16, v221
	v_mul_f32_e32 v32, 0xbfb8aa3b, v32
	v_exp_f32_e32 v32, v32
	s_waitcnt lgkmcnt(0)
	v_mfma_f32_32x32x16_bf16 v[16:31], v[36:39], v[40:43], v[16:31]
	v_add_f32_e32 v32, 1.0, v32
	v_div_scale_f32 v33, s[0:1], v32, v32, 1.0
	v_rcp_f32_e32 v34, v33
	s_nop 0
	v_fma_f32 v35, -v33, v34, 1.0
	v_fmac_f32_e32 v34, v35, v34
	v_div_scale_f32 v35, vcc, 1.0, v32, 1.0
	v_mul_f32_e32 v36, v35, v34
	v_fma_f32 v37, -v33, v36, v35
	v_fmac_f32_e32 v36, v37, v34
	v_fma_f32 v33, -v33, v36, v35
	v_div_fmas_f32 v33, v33, v34, v36
	v_div_fixup_f32 v32, v33, v32, 1.0
	v_mul_f32_e32 v0, v0, v32
	v_mul_f32_e32 v1, v1, v32
	v_mul_f32_e32 v2, v2, v32
	v_mul_f32_e32 v3, v3, v32
	v_cvt_pk_bf16_f32 v232, v0, v1
	v_cvt_pk_bf16_f32 v233, v2, v3
	v_mul_f32_e32 v16, v16, v32
	v_mul_f32_e32 v17, v17, v32
	v_mul_f32_e32 v18, v18, v32
	v_mul_f32_e32 v19, v19, v32
	v_mul_f32_e32 v4, v4, v32
	v_mul_f32_e32 v5, v5, v32
	v_mul_f32_e32 v6, v6, v32
	v_mul_f32_e32 v7, v7, v32
	v_cvt_pk_bf16_f32 v240, v16, v17
	v_cvt_pk_bf16_f32 v241, v18, v19
	s_nop 0
	s_nop 0
	v_cvt_pk_bf16_f32 v234, v4, v5
	v_cvt_pk_bf16_f32 v235, v6, v7
	v_mul_f32_e32 v20, v20, v32
	v_mul_f32_e32 v21, v21, v32
	v_mul_f32_e32 v22, v22, v32
	v_mul_f32_e32 v23, v23, v32
	v_mul_f32_e32 v8, v8, v32
	v_mul_f32_e32 v9, v9, v32
	v_mul_f32_e32 v10, v10, v32
	v_mul_f32_e32 v11, v11, v32
	v_cvt_pk_bf16_f32 v242, v20, v21
	v_cvt_pk_bf16_f32 v243, v22, v23
	v_and_b32_e32 v248, 32, v200
	v_lshrrev_b32_e32 v248, 2, v248
	v_mov_b32_e32 v249, 0
	v_lshl_add_u64 v[248:249], v[70:71], 0, v[248:249]
	v_permlane32_swap_b32_e32 v232, v234
	v_permlane32_swap_b32_e32 v233, v235
	global_store_dwordx4 v[248:249], v[232:235], off offset:-64
	s_nop 1
	v_permlane32_swap_b32_e32 v240, v242
	v_permlane32_swap_b32_e32 v241, v243
	global_store_dwordx4 v[248:249], v[240:243], off
	v_cvt_pk_bf16_f32 v236, v8, v9
	v_cvt_pk_bf16_f32 v237, v10, v11
	v_mul_f32_e32 v24, v24, v32
	v_mul_f32_e32 v25, v25, v32
	v_mul_f32_e32 v26, v26, v32
	v_mul_f32_e32 v27, v27, v32
	v_mul_f32_e32 v12, v12, v32
	v_mul_f32_e32 v13, v13, v32
	v_mul_f32_e32 v14, v14, v32
	v_mul_f32_e32 v15, v15, v32
	v_cvt_pk_bf16_f32 v244, v24, v25
	v_cvt_pk_bf16_f32 v245, v26, v27
	s_nop 0
	s_nop 0
	v_cvt_pk_bf16_f32 v238, v12, v13
	v_cvt_pk_bf16_f32 v239, v14, v15
	v_mul_f32_e32 v28, v28, v32
	v_mul_f32_e32 v29, v29, v32
	v_mul_f32_e32 v30, v30, v32
	v_mul_f32_e32 v31, v31, v32
	v_cvt_pk_bf16_f32 v246, v28, v29
	v_cvt_pk_bf16_f32 v247, v30, v31
	v_permlane32_swap_b32_e32 v236, v238
	v_permlane32_swap_b32_e32 v237, v239
	global_store_dwordx4 v[248:249], v[236:239], off offset:-32
	s_nop 1
	v_permlane32_swap_b32_e32 v244, v246
	v_permlane32_swap_b32_e32 v245, v247
	global_store_dwordx4 v[248:249], v[244:247], off offset:32
	v_lshl_add_u64 v[70:71], v[70:71], 0, s[14:15]
	s_cbranch_scc1 .LBB0_544
.LBB0_518:
	s_waitcnt vmcnt(4)
.Lnsa1_enter:
	v_mov_b32_e32 v221, v220
	v_mov_b64_e32 v[0:1], v[204:205]
	v_mov_b64_e32 v[2:3], v[206:207]
	v_mov_b64_e32 v[72:73], v[208:209]
	v_mov_b64_e32 v[74:75], v[210:211]
	ds_read_b128 v[4:7], v162
	ds_read_b128 v[76:79], v162 offset:32
	v_readfirstlane_b32 s0, v94
	s_mov_b64 s[4:5], -1
	s_cmpk_lt_i32 s0, 0x28f
	s_waitcnt lgkmcnt(1)
	v_mfma_f32_32x32x16_bf16 v[48:63], v[4:7], v[0:3], 0
	ds_read_b128 v[4:7], v162 offset:4608
	ds_read_b128 v[80:83], v162 offset:4640
	s_waitcnt lgkmcnt(1)
	v_mfma_f32_32x32x16_bf16 v[32:47], v[4:7], v[0:3], 0
	ds_read_b128 v[4:7], v162 offset:9216
	ds_read_b128 v[84:87], v162 offset:9248
	s_waitcnt lgkmcnt(1)
	v_mfma_f32_32x32x16_bf16 v[16:31], v[4:7], v[0:3], 0
	ds_read_b128 v[4:7], v162 offset:13824
	ds_read_b128 v[164:167], v162 offset:13856
	v_mov_b64_e32 v[168:169], v[216:217]
	v_mov_b64_e32 v[170:171], v[218:219]
	v_mfma_f32_32x32x16_bf16 v[48:63], v[76:79], v[72:75], v[48:63]
	v_mov_b64_e32 v[76:77], v[212:213]
	v_mov_b64_e32 v[78:79], v[214:215]
	global_load_dwordx4 v[204:207], v[68:69], off offset:64
	global_load_dwordx4 v[208:211], v[68:69], off offset:96
	global_load_dwordx4 v[212:215], v[68:69], off offset:128
	global_load_dwordx4 v[216:219], v[68:69], off offset:160
	global_load_ushort v220, v[66:67], off offset:6
	s_waitcnt lgkmcnt(1)
	v_mfma_f32_32x32x16_bf16 v[0:15], v[4:7], v[0:3], 0
	v_mfma_f32_32x32x16_bf16 v[32:47], v[80:83], v[72:75], v[32:47]
	v_mfma_f32_32x32x16_bf16 v[16:31], v[84:87], v[72:75], v[16:31]
	s_waitcnt lgkmcnt(0)
	v_mfma_f32_32x32x16_bf16 v[0:15], v[164:167], v[72:75], v[0:15]
	ds_read_b128 v[72:75], v162 offset:64
	ds_read_b128 v[80:83], v162 offset:96
	s_waitcnt lgkmcnt(1)
	v_mfma_f32_32x32x16_bf16 v[48:63], v[72:75], v[76:79], v[48:63]
	ds_read_b128 v[72:75], v162 offset:4672
	ds_read_b128 v[84:87], v162 offset:4704
	s_waitcnt lgkmcnt(1)
	v_mfma_f32_32x32x16_bf16 v[32:47], v[72:75], v[76:79], v[32:47]
	ds_read_b128 v[72:75], v162 offset:9280
	ds_read_b128 v[164:167], v162 offset:9312
	s_waitcnt lgkmcnt(1)
	v_mfma_f32_32x32x16_bf16 v[16:31], v[72:75], v[76:79], v[16:31]
	ds_read_b128 v[72:75], v162 offset:13888
	ds_read_b128 v[172:175], v162 offset:13920
	s_waitcnt lgkmcnt(1)
	v_mfma_f32_32x32x16_bf16 v[0:15], v[72:75], v[76:79], v[0:15]
	v_mfma_f32_32x32x16_bf16 v[48:63], v[80:83], v[168:171], v[48:63]
	v_mfma_f32_32x32x16_bf16 v[32:47], v[84:87], v[168:171], v[32:47]
	v_mfma_f32_32x32x16_bf16 v[16:31], v[164:167], v[168:171], v[16:31]
	s_waitcnt lgkmcnt(0)
	v_mfma_f32_32x32x16_bf16 v[0:15], v[172:175], v[168:171], v[0:15]
	s_cbranch_scc1 .LBB0_520
	s_add_i32 s1, s20, 0
	v_mov_b32_e32 v72, s1
	ds_read_b32 v82, v72 offset:43524
	s_mov_b64 s[4:5], 0
	s_waitcnt lgkmcnt(0)
	s_nop 1
	v_pk_add_f32 v[78:79], v[48:49], v[82:83] op_sel_hi:[1,0]
	v_pk_add_f32 v[76:77], v[50:51], v[82:83] op_sel_hi:[1,0]
	v_max3_f32 v80, v78, s71, v79
	v_pk_add_f32 v[72:73], v[52:53], v[82:83] op_sel_hi:[1,0]
	v_max3_f32 v80, v80, v76, v77
	v_pk_add_f32 v[74:75], v[54:55], v[82:83] op_sel_hi:[1,0]
	v_max3_f32 v80, v80, v72, v73
	v_pk_add_f32 v[84:85], v[56:57], v[82:83] op_sel_hi:[1,0]
	v_max3_f32 v80, v80, v74, v75
	v_max3_f32 v80, v80, v84, v85
	v_pk_add_f32 v[86:87], v[58:59], v[82:83] op_sel_hi:[1,0]
	s_nop 0
	v_max3_f32 v83, v80, v86, v87
	v_pk_add_f32 v[80:81], v[60:61], v[82:83] op_sel_hi:[1,0]
	s_nop 0
	v_max3_f32 v164, v83, v80, v81
	v_pk_add_f32 v[82:83], v[62:63], v[82:83] op_sel_hi:[1,0]
	s_nop 0
	v_max3_f32 v164, v164, v82, v83

.LBB0_556:
	v_fma_f32 v64, v64, s20, -v197
	v_exp_f32_e32 v131, v64
	v_fma_f32 v64, v113, s20, -v170
	v_fma_f32 v96, v96, s20, -v197
	v_exp_f32_e32 v113, v64
	v_fma_f32 v64, v97, s20, -v197
	v_fma_f32 v112, v112, s20, -v170
	v_exp_f32_e32 v130, v96
	v_exp_f32_e32 v96, v64
	v_fma_f32 v64, v81, s20, -v170
	v_fma_f32 v66, v66, s20, -v197
	v_exp_f32_e32 v129, v112
	v_exp_f32_e32 v112, v64
	v_fma_f32 v64, v65, s20, -v197
	v_exp_f32_e32 v133, v66
	v_fma_f32 v66, v115, s20, -v170
	v_exp_f32_e32 v97, v64
	v_fma_f32 v64, v114, s20, -v170
	v_exp_f32_e32 v81, v66
	v_fma_f32 v66, v99, s20, -v197
	v_fma_f32 v80, v80, s20, -v170
	v_exp_f32_e32 v65, v64
	v_fma_f32 v64, v98, s20, -v197
	v_exp_f32_e32 v98, v66
	v_fma_f32 v66, v83, s20, -v170
	v_fma_f32 v68, v68, s20, -v197
	v_exp_f32_e32 v128, v80
	v_exp_f32_e32 v80, v66
	v_fma_f32 v66, v67, s20, -v197
	v_exp_f32_e32 v115, v68
	v_fma_f32 v68, v117, s20, -v170
	v_exp_f32_e32 v99, v66
	v_fma_f32 v66, v116, s20, -v170
	v_exp_f32_e32 v83, v68
	v_fma_f32 v68, v101, s20, -v197
	v_exp_f32_e32 v67, v66
	v_fma_f32 v66, v100, s20, -v197
	v_exp_f32_e32 v100, v68
	v_fma_f32 v68, v85, s20, -v170
	v_exp_f32_e32 v132, v64
	v_fma_f32 v64, v82, s20, -v170
	v_exp_f32_e32 v82, v68
	v_fma_f32 v68, v69, s20, -v197
	v_exp_f32_e32 v114, v66
	v_fma_f32 v66, v84, s20, -v170
	v_exp_f32_e32 v101, v68
	v_fma_f32 v68, v118, s20, -v170
	v_fma_f32 v84, v119, s20, -v170
	v_exp_f32_e32 v69, v68
	v_fma_f32 v68, v102, s20, -v197
	v_exp_f32_e32 v85, v84
	v_fma_f32 v84, v103, s20, -v197
	v_exp_f32_e32 v116, v68
	v_fma_f32 v68, v86, s20, -v170
	v_exp_f32_e32 v86, v84
	v_fma_f32 v84, v120, s20, -v170
	v_exp_f32_e32 v103, v84
	v_fma_f32 v84, v104, s20, -v197
	v_exp_f32_e32 v120, v84
	v_fma_f32 v84, v121, s20, -v170
	v_exp_f32_e32 v119, v84
	v_fma_f32 v84, v105, s20, -v197
	v_exp_f32_e32 v134, v84
	v_fma_f32 v84, v122, s20, -v170
	v_exp_f32_e32 v105, v84
	v_fma_f32 v84, v106, s20, -v197
	v_exp_f32_e32 v106, v84
	v_fma_f32 v84, v123, s20, -v170
	v_exp_f32_e32 v153, v84
	v_fma_f32 v84, v107, s20, -v197
	v_cvt_pk_bf16_f32 v136, v129, v113
	v_cvt_pk_bf16_f32 v137, v65, v81
	v_cvt_pk_bf16_f32 v138, v67, v83
	v_cvt_pk_bf16_f32 v139, v69, v85
	v_cvt_pk_bf16_f32 v140, v130, v96
	v_cvt_pk_bf16_f32 v141, v132, v98
	v_cvt_pk_bf16_f32 v142, v114, v100
	v_cvt_pk_bf16_f32 v143, v116, v86
	ds_read_b64_tr_b16 v[144:145], v179 offset:30720
	ds_read_b64_tr_b16 v[146:147], v179 offset:32256
	v_exp_f32_e32 v154, v84
	v_fma_f32 v84, v124, s20, -v170
	v_exp_f32_e32 v157, v84
	v_fma_f32 v84, v108, s20, -v197
	v_exp_f32_e32 v158, v84
	v_fma_f32 v84, v125, s20, -v170
	v_exp_f32_e32 v161, v84
	v_fma_f32 v84, v109, s20, -v197
	v_exp_f32_e32 v162, v84
	v_fma_f32 v84, v126, s20, -v170
	s_waitcnt lgkmcnt(0)
	v_mfma_f32_32x32x16_bf16 v[48:63], v[144:147], v[136:139], v[48:63]
	v_fma_f32 v70, v70, s20, -v197
	v_exp_f32_e32 v117, v70
	v_fma_f32 v70, v87, s20, -v170
	ds_read_b64_tr_b16 v[150:151], v179 offset:32320
	ds_read_b64_tr_b16 v[148:149], v179 offset:30784
	v_exp_f32_e32 v64, v64
	v_exp_f32_e32 v66, v66
	v_exp_f32_e32 v68, v68
	v_mfma_f32_32x32x16_bf16 v[0:15], v[144:147], v[140:143], v[0:15]
	v_exp_f32_e32 v145, v84
	v_fma_f32 v84, v110, s20, -v197
	v_exp_f32_e32 v126, v84
	v_fma_f32 v84, v127, s20, -v170
	v_exp_f32_e32 v147, v84
	v_fma_f32 v84, v111, s20, -v197
	v_exp_f32_e32 v164, v84
	v_exp_f32_e32 v84, v70
	v_fma_f32 v70, v71, s20, -v197
	v_exp_f32_e32 v87, v70
	v_fma_f32 v70, v88, s20, -v170
	v_exp_f32_e32 v102, v70
	v_fma_f32 v70, v72, s20, -v197
	v_exp_f32_e32 v121, v70
	v_fma_f32 v70, v89, s20, -v170
	v_exp_f32_e32 v118, v70
	v_fma_f32 v70, v73, s20, -v197
	v_exp_f32_e32 v135, v70
	v_fma_f32 v70, v90, s20, -v170
	v_exp_f32_e32 v104, v70
	v_fma_f32 v70, v74, s20, -v197
	v_fma_f32 v74, v91, s20, -v170
	v_exp_f32_e32 v152, v74
	v_fma_f32 v74, v75, s20, -v197
	v_exp_f32_e32 v155, v74
	v_fma_f32 v74, v92, s20, -v170
	v_exp_f32_e32 v156, v74
	v_fma_f32 v74, v76, s20, -v197
	v_exp_f32_e32 v159, v74
	v_fma_f32 v74, v93, s20, -v170
	v_exp_f32_e32 v160, v74
	v_fma_f32 v74, v77, s20, -v197
	v_exp_f32_e32 v163, v74
	v_fma_f32 v74, v94, s20, -v170
	v_exp_f32_e32 v144, v74
	v_fma_f32 v74, v78, s20, -v197
	v_exp_f32_e32 v127, v74
	v_fma_f32 v74, v95, s20, -v170
	v_exp_f32_e32 v146, v74
	v_fma_f32 v74, v79, s20, -v197
	v_pk_add_f32 v[78:79], v[130:131], 0 op_sel_hi:[1,0]
	s_waitcnt lgkmcnt(0)
	v_mfma_f32_32x32x16_bf16 v[32:47], v[148:151], v[136:139], v[32:47]
	v_add_f32_e64 v78, v96, v78
	v_add_f32_e64 v79, v97, v79
	v_cvt_pk_bf16_f32 v108, v103, v119
	v_cvt_pk_bf16_f32 v109, v105, v153
	v_cvt_pk_bf16_f32 v110, v157, v161
	v_cvt_pk_bf16_f32 v111, v145, v147
	v_cvt_pk_bf16_f32 v122, v120, v134
	v_add_f32_e64 v78, v132, v78
	v_add_f32_e64 v79, v133, v79
	v_cvt_pk_bf16_f32 v123, v106, v154
	v_cvt_pk_bf16_f32 v124, v158, v162
	v_cvt_pk_bf16_f32 v125, v126, v164
	ds_read_b64_tr_b16 v[136:137], v179 offset:33792
	ds_read_b64_tr_b16 v[138:139], v179 offset:35328
	v_pk_add_f32 v[78:79], v[98:99], v[78:79]
	v_mfma_f32_32x32x16_bf16 v[16:31], v[148:151], v[140:143], v[16:31]
	v_add_f32_e64 v78, v114, v78
	v_add_f32_e64 v79, v115, v79
	ds_read_b64_tr_b16 v[142:143], v179 offset:35392
	ds_read_b64_tr_b16 v[140:141], v179 offset:33856
	v_add_f32_e64 v78, v100, v78
	v_add_f32_e64 v79, v101, v79
	v_exp_f32_e32 v107, v70
	v_pk_add_f32 v[78:79], v[116:117], v[78:79]
	v_cvt_pk_bf16_f32 v70, v128, v112
	v_cvt_pk_bf16_f32 v71, v64, v80
	v_cvt_pk_bf16_f32 v72, v66, v82
	v_cvt_pk_bf16_f32 v73, v68, v84
	v_cvt_pk_bf16_f32 v88, v131, v97
	v_cvt_pk_bf16_f32 v89, v133, v99
	v_cvt_pk_bf16_f32 v90, v115, v101
	v_cvt_pk_bf16_f32 v91, v117, v87
	s_nop 0
	v_pk_add_f32 v[78:79], v[86:87], v[78:79]
	v_pk_add_f32 v[86:87], v[128:129], 0 op_sel_hi:[1,0]
	s_waitcnt lgkmcnt(0)
	v_mfma_f32_32x32x16_bf16 v[32:47], v[140:143], v[108:111], v[32:47]
	v_add_f32_e64 v86, v112, v86
	v_add_f32_e64 v87, v113, v87
	v_add_f32_e64 v78, v120, v78
	v_add_f32_e64 v79, v121, v79
	v_add_f32_e64 v64, v64, v86
	v_add_f32_e64 v65, v65, v87
	v_pk_add_f32 v[78:79], v[134:135], v[78:79]
	v_pk_add_f32 v[64:65], v[80:81], v[64:65]
	v_pk_add_f32 v[78:79], v[106:107], v[78:79]
	v_pk_add_f32 v[64:65], v[66:67], v[64:65]
	v_mfma_f32_32x32x16_bf16 v[48:63], v[136:139], v[108:111], v[48:63]
	v_add_f32_e64 v64, v82, v64
	v_add_f32_e64 v65, v83, v65
	ds_read_b64_tr_b16 v[108:109], v179 offset:36864
	ds_read_b64_tr_b16 v[110:111], v179 offset:38400
	v_add_f32_e64 v64, v68, v64
	v_add_f32_e64 v65, v69, v65
	v_exp_f32_e32 v165, v74
	v_pk_add_f32 v[64:65], v[84:85], v[64:65]
	v_pk_add_f32 v[78:79], v[154:155], v[78:79]
	v_pk_add_f32 v[64:65], v[102:103], v[64:65]
	v_mfma_f32_32x32x16_bf16 v[0:15], v[136:139], v[122:125], v[0:15]
	v_add_f32_e64 v64, v118, v64
	v_add_f32_e64 v65, v119, v65
	v_add_f32_e64 v78, v158, v78
	v_add_f32_e64 v79, v159, v79
	v_add_f32_e64 v64, v104, v64
	v_add_f32_e64 v65, v105, v65
	v_pk_add_f32 v[78:79], v[162:163], v[78:79]
	v_pk_add_f32 v[64:65], v[152:153], v[64:65]
	v_pk_add_f32 v[78:79], v[126:127], v[78:79]
	v_pk_add_f32 v[64:65], v[156:157], v[64:65]
	v_mfma_f32_32x32x16_bf16 v[16:31], v[140:143], v[122:125], v[16:31]
	v_add_f32_e64 v64, v160, v64
	v_add_f32_e64 v65, v161, v65
	ds_read_b64_tr_b16 v[124:125], v179 offset:38464
	ds_read_b64_tr_b16 v[122:123], v179 offset:36928
	v_add_f32_e64 v64, v144, v64
	v_add_f32_e64 v65, v145, v65
	s_lshl_b32 s6, s34, 1
	v_pk_add_f32 v[64:65], v[146:147], v[64:65]
	v_lshlrev_b32_e32 v170, 3, v195
	v_add_f32_e32 v64, v64, v65
	v_add_f32_e32 v66, v175, v64
	ds_bpermute_b32 v67, v196, v66
	s_waitcnt lgkmcnt(1)
	v_mfma_f32_32x32x16_bf16 v[32:47], v[122:125], v[70:73], v[32:47]
	v_add_f32_e64 v64, v164, v78
	v_add_f32_e64 v65, v165, v79
	s_add_i32 s17, s17, s30
	v_add_f32_e32 v64, v64, v65
	s_waitcnt lgkmcnt(0)
	v_add_f32_e32 v65, v66, v67
	v_max_f32_e32 v65, 0xda24260, v65
	v_div_scale_f32 v66, s[0:1], v65, v65, 1.0
	v_mfma_f32_32x32x16_bf16 v[48:63], v[108:111], v[70:73], v[48:63]
	v_cvt_pk_bf16_f32 v70, v102, v118
	v_cvt_pk_bf16_f32 v71, v104, v152
	v_cvt_pk_bf16_f32 v72, v156, v160
	v_cvt_pk_bf16_f32 v73, v144, v146
	v_cvt_pk_bf16_f32 v74, v121, v135
	v_cvt_pk_bf16_f32 v75, v107, v155
	v_cvt_pk_bf16_f32 v76, v159, v163
	v_mfma_f32_32x32x16_bf16 v[0:15], v[108:111], v[88:91], v[0:15]
	v_cvt_pk_bf16_f32 v77, v127, v165
	ds_read_b64_tr_b16 v[92:93], v179 offset:39936
	ds_read_b64_tr_b16 v[94:95], v179 offset:41472
	v_rcp_f32_e32 v67, v66
	v_add_f32_e32 v64, v174, v64
	s_cmpk_lt_i32 s17, 0x200
	v_fma_f32 v68, -v66, v67, 1.0
	v_mfma_f32_32x32x16_bf16 v[16:31], v[122:125], v[88:91], v[16:31]
	ds_read_b64_tr_b16 v[90:91], v179 offset:41536
	ds_read_b64_tr_b16 v[88:89], v179 offset:40000
	v_fmac_f32_e32 v67, v68, v67
	v_div_scale_f32 v68, vcc, 1.0, v65, 1.0
	v_mul_f32_e32 v69, v68, v67
	s_waitcnt lgkmcnt(0)
	s_barrier
	v_mfma_f32_32x32x16_bf16 v[32:47], v[88:91], v[70:73], v[32:47]
	v_mfma_f32_32x32x16_bf16 v[48:63], v[92:95], v[70:73], v[48:63]
	v_fma_f32 v70, -v66, v69, v68
	v_fmac_f32_e32 v69, v70, v67
	v_fma_f32 v66, -v66, v69, v68
	v_div_fmas_f32 v66, v66, v67, v69
	v_div_fixup_f32 v65, v66, v65, 1.0
	s_nop 5
	v_mul_f32_e32 v66, v32, v65
	v_mul_f32_e32 v67, v33, v65
	v_lshlrev_b64 v[32:33], 11, v[172:173]
	v_mul_f32_e32 v68, v34, v65
	v_mul_f32_e32 v69, v35, v65
	v_lshl_add_u64 v[34:35], s[4:5], 0, v[32:33]
	v_lshl_add_u64 v[34:35], v[34:35], 0, s[6:7]
	v_mul_f32_e32 v48, v48, v65
	v_mul_f32_e32 v49, v49, v65
	v_mul_f32_e32 v50, v50, v65
	v_mul_f32_e32 v51, v51, v65
	v_mul_f32_e32 v70, v36, v65
	v_mul_f32_e32 v71, v37, v65
	v_mul_f32_e32 v72, v38, v65
	v_lshl_add_u64 v[34:35], v[34:35], 0, v[170:171]
	v_cvt_pk_bf16_f32 v232, v48, v49
	v_cvt_pk_bf16_f32 v233, v50, v51
	v_cvt_pk_bf16_f32 v240, v66, v67
	v_mul_f32_e32 v52, v52, v65
	v_mul_f32_e32 v53, v53, v65
	v_mul_f32_e32 v54, v54, v65
	v_mul_f32_e32 v55, v55, v65
	v_mul_f32_e32 v73, v39, v65
	v_mul_f32_e32 v40, v40, v65
	v_cvt_pk_bf16_f32 v241, v68, v69
	s_nop 0
	s_nop 0
	v_cvt_pk_bf16_f32 v234, v52, v53
	v_cvt_pk_bf16_f32 v235, v54, v55
	v_cvt_pk_bf16_f32 v242, v70, v71
	v_mul_f32_e32 v56, v56, v65
	v_mul_f32_e32 v57, v57, v65
	v_mul_f32_e32 v41, v41, v65
	v_mul_f32_e32 v58, v58, v65
	v_mul_f32_e32 v59, v59, v65
	v_cvt_pk_bf16_f32 v243, v72, v73
	v_and_b32_e32 v248, 32, v200
	v_lshrrev_b32_e32 v248, 2, v248
	v_mov_b32_e32 v249, 0
	v_lshl_add_u64 v[248:249], v[34:35], 0, v[248:249]
	v_permlane32_swap_b32_e32 v232, v234
	v_permlane32_swap_b32_e32 v233, v235
	global_store_dwordx4 v[248:249], v[232:235], off offset:1536
	s_nop 1
	v_permlane32_swap_b32_e32 v240, v242
	v_permlane32_swap_b32_e32 v241, v243
	global_store_dwordx4 v[248:249], v[240:243], off offset:1600
	v_cvt_pk_bf16_f32 v236, v56, v57
	v_cvt_pk_bf16_f32 v237, v58, v59
	v_cvt_pk_bf16_f32 v244, v40, v41
	ds_bpermute_b32 v40, v196, v64
	v_mul_f32_e32 v42, v42, v65
	v_mul_f32_e32 v43, v43, v65
	v_cvt_pk_bf16_f32 v245, v42, v43
	s_nop 0
	s_waitcnt lgkmcnt(0)
	v_add_f32_e32 v39, v64, v40
	v_max_f32_e32 v40, 0xda24260, v39
	v_div_scale_f32 v41, s[0:1], v40, v40, 1.0
	v_rcp_f32_e32 v42, v41
	v_mul_f32_e32 v60, v60, v65
	v_mul_f32_e32 v61, v61, v65
	v_mul_f32_e32 v62, v62, v65
	v_mul_f32_e32 v63, v63, v65
	s_nop 0
	v_cvt_pk_bf16_f32 v238, v60, v61
	v_cvt_pk_bf16_f32 v239, v62, v63
	v_mfma_f32_32x32x16_bf16 v[0:15], v[92:95], v[74:77], v[0:15]
	v_mul_f32_e32 v44, v44, v65
	v_mul_f32_e32 v45, v45, v65
	v_mul_f32_e32 v46, v46, v65
	v_mul_f32_e32 v47, v47, v65
	v_cvt_pk_bf16_f32 v246, v44, v45
	v_cvt_pk_bf16_f32 v247, v46, v47
	v_permlane32_swap_b32_e32 v236, v238
	v_permlane32_swap_b32_e32 v237, v239
	global_store_dwordx4 v[248:249], v[236:239], off offset:1568
	s_nop 1
	v_permlane32_swap_b32_e32 v244, v246
	v_permlane32_swap_b32_e32 v245, v247
	global_store_dwordx4 v[248:249], v[244:247], off offset:1632
	v_fma_f32 v34, -v41, v42, 1.0
	v_fmac_f32_e32 v42, v34, v42
	v_div_scale_f32 v34, vcc, 1.0, v40, 1.0
	v_mfma_f32_32x32x16_bf16 v[16:31], v[88:91], v[74:77], v[16:31]
	v_mul_f32_e32 v35, v34, v42
	v_fma_f32 v36, -v41, v35, v34
	v_fmac_f32_e32 v35, v36, v42
	v_fma_f32 v34, -v41, v35, v34
	v_div_fmas_f32 v34, v34, v42, v35
	v_div_fixup_f32 v34, v34, v40, 1.0
	v_or_b32_e32 v32, 0x10000, v32
	v_mul_f32_e32 v35, v0, v34
	v_mul_f32_e32 v36, v1, v34
	v_lshl_add_u64 v[0:1], s[4:5], 0, v[32:33]
	v_mul_f32_e32 v3, v3, v34
	v_lshl_add_u64 v[0:1], v[0:1], 0, s[6:7]
	v_mul_f32_e32 v16, v16, v34
	v_mul_f32_e32 v17, v17, v34
	v_mul_f32_e32 v37, v2, v34
	v_mul_f32_e32 v18, v18, v34
	v_mul_f32_e32 v19, v19, v34
	v_mul_f32_e32 v38, v4, v34
	v_mul_f32_e32 v39, v5, v34
	v_lshl_add_u64 v[0:1], v[0:1], 0, v[170:171]
	v_cvt_pk_bf16_f32 v232, v35, v36
	v_cvt_pk_bf16_f32 v233, v37, v3
	v_cvt_pk_bf16_f32 v240, v16, v17
	v_cvt_pk_bf16_f32 v241, v18, v19
	v_mul_f32_e32 v20, v20, v34
	v_mul_f32_e32 v21, v21, v34
	v_mul_f32_e32 v6, v6, v34
	v_mul_f32_e32 v22, v22, v34
	v_mul_f32_e32 v7, v7, v34
	v_mul_f32_e32 v23, v23, v34
	s_nop 0
	s_nop 0
	v_cvt_pk_bf16_f32 v234, v38, v39
	v_cvt_pk_bf16_f32 v235, v6, v7
	v_cvt_pk_bf16_f32 v242, v20, v21
	v_cvt_pk_bf16_f32 v243, v22, v23
	v_mul_f32_e32 v8, v8, v34
	v_mul_f32_e32 v24, v24, v34
	v_mul_f32_e32 v9, v9, v34
	v_mul_f32_e32 v25, v25, v34
	v_mul_f32_e32 v10, v10, v34
	v_mul_f32_e32 v26, v26, v34
	v_mul_f32_e32 v11, v11, v34
	v_mul_f32_e32 v27, v27, v34
	v_and_b32_e32 v248, 32, v200
	v_lshrrev_b32_e32 v248, 2, v248
	v_mov_b32_e32 v249, 0
	v_lshl_add_u64 v[248:249], v[0:1], 0, v[248:249]
	v_permlane32_swap_b32_e32 v232, v234
	v_permlane32_swap_b32_e32 v233, v235
	global_store_dwordx4 v[248:249], v[232:235], off offset:1536
	v_permlane32_swap_b32_e32 v240, v242
	v_permlane32_swap_b32_e32 v241, v243
	global_store_dwordx4 v[248:249], v[240:243], off offset:1600
	v_cvt_pk_bf16_f32 v236, v8, v9
	v_cvt_pk_bf16_f32 v237, v10, v11
	v_cvt_pk_bf16_f32 v244, v24, v25
	v_cvt_pk_bf16_f32 v245, v26, v27
	v_mul_f32_e32 v12, v12, v34
	v_mul_f32_e32 v28, v28, v34
	v_mul_f32_e32 v13, v13, v34
	v_mul_f32_e32 v29, v29, v34
	v_mul_f32_e32 v14, v14, v34
	v_mul_f32_e32 v30, v30, v34
	v_mul_f32_e32 v15, v15, v34
	v_mul_f32_e32 v31, v31, v34
	s_nop 0
	s_nop 0
	v_cvt_pk_bf16_f32 v238, v12, v13
	v_cvt_pk_bf16_f32 v239, v14, v15
	v_cvt_pk_bf16_f32 v246, v28, v29
	v_cvt_pk_bf16_f32 v247, v30, v31
	v_permlane32_swap_b32_e32 v236, v238
	v_permlane32_swap_b32_e32 v237, v239
	global_store_dwordx4 v[248:249], v[236:239], off offset:1568
	s_nop 1
	v_permlane32_swap_b32_e32 v244, v246
	v_permlane32_swap_b32_e32 v245, v247
	global_store_dwordx4 v[248:249], v[244:247], off offset:1632
	s_cbranch_scc0 .LBB0_563

.LBB0_625:
	global_load_ushort v0, v[154:155], off offset:2820
	global_load_dwordx2 v[66:67], v[146:147], off
	global_load_dwordx2 v[68:69], v[146:147], off offset:64
	global_load_dwordx2 v[70:71], v[146:147], off offset:16
	global_load_dwordx2 v[72:73], v[146:147], off offset:80
	global_load_dwordx2 v[74:75], v[146:147], off offset:32
	global_load_dwordx2 v[76:77], v[146:147], off offset:96
	global_load_dwordx2 v[78:79], v[146:147], off offset:48
	global_load_dwordx2 v[80:81], v[146:147], off offset:112
	global_load_dwordx2 v[206:207], v[148:149], off offset:64
	global_load_dwordx2 v[208:209], v[148:149], off
	global_load_dwordx2 v[210:211], v[148:149], off offset:16
	global_load_dwordx2 v[212:213], v[148:149], off offset:80
	global_load_dwordx2 v[214:215], v[148:149], off offset:32
	global_load_dwordx2 v[216:217], v[148:149], off offset:96
	global_load_dwordx2 v[218:219], v[148:149], off offset:112
	global_load_dwordx2 v[220:221], v[148:149], off offset:48
	global_load_ushort v224, v[152:153], off offset:2820
	ds_bpermute_b32 v82, v166, v151
	s_waitcnt lgkmcnt(0)
	v_add_f32_e32 v82, v151, v82
	v_max_f32_e32 v82, 0xda24260, v82
	v_div_scale_f32 v83, s[0:1], v82, v82, 1.0
	v_rcp_f32_e32 v84, v83
	v_div_scale_f32 v85, s[2:3], 1.0, v82, 1.0
	v_fma_f32 v86, -v83, v84, 1.0
	v_fmac_f32_e32 v84, v86, v84
	v_mul_f32_e32 v86, v85, v84
	v_fma_f32 v87, -v83, v86, v85
	v_fmac_f32_e32 v86, v87, v84
	v_fma_f32 v83, -v83, v86, v85
	s_waitcnt vmcnt(8)
	v_lshlrev_b32_e32 v0, 16, v0
	v_mul_f32_e32 v0, 0xbfb8aa3b, v0
	v_exp_f32_e32 v0, v0
	s_waitcnt vmcnt(7)
	v_lshlrev_b32_e32 v85, 16, v66
	v_and_b32_e32 v66, 0xffff0000, v66
	v_lshlrev_b32_e32 v87, 16, v67
	v_add_f32_e32 v0, 1.0, v0
	v_div_scale_f32 v100, s[0:1], v0, v0, 1.0
	v_rcp_f32_e32 v101, v100
	v_div_scale_f32 v103, vcc, 1.0, v0, 1.0
	v_and_b32_e32 v67, 0xffff0000, v67
	v_fma_f32 v104, -v100, v101, 1.0
	v_fmac_f32_e32 v101, v104, v101
	v_mul_f32_e32 v104, v103, v101
	v_fma_f32 v105, -v100, v104, v103
	v_fmac_f32_e32 v104, v105, v101
	v_fma_f32 v100, -v100, v104, v103
	v_div_fmas_f32 v100, v100, v101, v104
	s_mov_b64 vcc, s[2:3]
	v_div_fmas_f32 v83, v83, v84, v86
	v_div_fixup_f32 v0, v100, v0, 1.0
	v_div_fixup_f32 v82, v83, v82, 1.0
	s_waitcnt vmcnt(6)
	v_lshlrev_b32_e32 v88, 16, v68
	v_and_b32_e32 v68, 0xffff0000, v68
	v_mul_f32_e32 v0, v82, v0
	v_lshlrev_b32_e32 v89, 16, v69
	v_and_b32_e32 v69, 0xffff0000, v69
	s_waitcnt vmcnt(5)
	v_lshlrev_b32_e32 v90, 16, v70
	v_and_b32_e32 v70, 0xffff0000, v70
	v_lshlrev_b32_e32 v91, 16, v71
	v_and_b32_e32 v71, 0xffff0000, v71
	v_fmac_f32_e32 v85, v50, v0
	v_fmac_f32_e32 v66, v51, v0
	v_fmac_f32_e32 v87, v52, v0
	v_fmac_f32_e32 v67, v53, v0
	v_fmac_f32_e32 v88, v34, v0
	v_fmac_f32_e32 v68, v35, v0
	v_cvt_pk_bf16_f32 v232, v85, v66
	v_cvt_pk_bf16_f32 v233, v87, v67
	s_waitcnt vmcnt(4)
	v_lshlrev_b32_e32 v92, 16, v72
	v_and_b32_e32 v72, 0xffff0000, v72
	v_lshlrev_b32_e32 v93, 16, v73
	v_and_b32_e32 v73, 0xffff0000, v73
	s_waitcnt vmcnt(3)
	v_lshlrev_b32_e32 v94, 16, v74
	v_and_b32_e32 v74, 0xffff0000, v74
	v_lshlrev_b32_e32 v95, 16, v75
	v_and_b32_e32 v75, 0xffff0000, v75
	v_fmac_f32_e32 v89, v36, v0
	v_fmac_f32_e32 v69, v37, v0
	v_fmac_f32_e32 v90, v54, v0
	v_fmac_f32_e32 v70, v55, v0
	v_fmac_f32_e32 v91, v56, v0
	v_fmac_f32_e32 v71, v57, v0
	v_cvt_pk_bf16_f32 v240, v88, v68
	v_cvt_pk_bf16_f32 v241, v89, v69
	s_nop 0
	s_nop 0
	v_cvt_pk_bf16_f32 v234, v90, v70
	v_cvt_pk_bf16_f32 v235, v91, v71
	s_waitcnt vmcnt(2)
	v_lshlrev_b32_e32 v96, 16, v76
	v_and_b32_e32 v76, 0xffff0000, v76
	v_lshlrev_b32_e32 v97, 16, v77
	v_and_b32_e32 v77, 0xffff0000, v77
	s_waitcnt vmcnt(1)
	v_lshlrev_b32_e32 v98, 16, v78
	v_and_b32_e32 v78, 0xffff0000, v78
	v_lshlrev_b32_e32 v99, 16, v79
	v_and_b32_e32 v79, 0xffff0000, v79
	v_fmac_f32_e32 v92, v38, v0
	v_fmac_f32_e32 v72, v39, v0
	v_fmac_f32_e32 v93, v40, v0
	v_fmac_f32_e32 v73, v41, v0
	v_fmac_f32_e32 v94, v58, v0
	v_fmac_f32_e32 v74, v59, v0
	v_fmac_f32_e32 v95, v60, v0
	v_fmac_f32_e32 v75, v61, v0
	s_waitcnt vmcnt(0)
	v_and_b32_e32 v38, 0xffff0000, v80
	v_lshlrev_b32_e32 v39, 16, v81
	v_and_b32_e32 v40, 0xffff0000, v81
	v_cvt_pk_bf16_f32 v242, v92, v72
	v_cvt_pk_bf16_f32 v243, v93, v73
	v_and_b32_e32 v248, 32, v200
	v_lshrrev_b32_e32 v248, 2, v248
	v_mov_b32_e32 v249, 0
	v_lshl_add_u64 v[248:249], v[146:147], 0, v[248:249]
	v_permlane32_swap_b32_e32 v232, v234
	v_permlane32_swap_b32_e32 v233, v235
	global_store_dwordx4 v[248:249], v[232:235], off
	s_nop 1
	v_permlane32_swap_b32_e32 v240, v242
	v_permlane32_swap_b32_e32 v241, v243
	global_store_dwordx4 v[248:249], v[240:243], off offset:64
	v_cvt_pk_bf16_f32 v236, v94, v74
	v_cvt_pk_bf16_f32 v237, v95, v75
	v_lshlrev_b32_e32 v102, 16, v80
	v_fmac_f32_e32 v96, v42, v0
	v_fmac_f32_e32 v76, v43, v0
	v_fmac_f32_e32 v97, v44, v0
	v_fmac_f32_e32 v77, v45, v0
	v_fmac_f32_e32 v98, v62, v0
	v_fmac_f32_e32 v78, v63, v0
	v_fmac_f32_e32 v99, v64, v0
	v_fmac_f32_e32 v79, v65, v0
	v_fmac_f32_e32 v38, v47, v0
	v_fmac_f32_e32 v39, v48, v0
	v_fmac_f32_e32 v40, v49, v0
	v_cvt_pk_bf16_f32 v244, v96, v76
	v_cvt_pk_bf16_f32 v245, v97, v77
	s_nop 0
	s_nop 0
	v_cvt_pk_bf16_f32 v238, v98, v78
	v_cvt_pk_bf16_f32 v239, v99, v79
	v_fmac_f32_e32 v102, v46, v0
	v_cvt_pk_bf16_f32 v246, v102, v38
	v_cvt_pk_bf16_f32 v247, v39, v40
	s_waitcnt vmcnt(2)
	v_mov_b64_e32 v[38:39], v[206:207]
	v_mov_b64_e32 v[40:41], v[212:213]
	s_nop 0
	v_permlane32_swap_b32_e32 v236, v238
	v_permlane32_swap_b32_e32 v237, v239
	global_store_dwordx4 v[248:249], v[236:239], off offset:32
	v_permlane32_swap_b32_e32 v244, v246
	v_permlane32_swap_b32_e32 v245, v247
	global_store_dwordx4 v[248:249], v[244:247], off offset:96
	v_mov_b32_e32 v0, v224
	s_nop 0
	v_mov_b64_e32 v[34:35], v[208:209]
	v_mov_b64_e32 v[36:37], v[210:211]
	v_mov_b64_e32 v[42:43], v[214:215]
	ds_bpermute_b32 v46, v166, v150
	v_mov_b64_e32 v[44:45], v[216:217]
	s_waitcnt lgkmcnt(0)
	v_add_f32_e32 v46, v150, v46
	v_max_f32_e32 v50, 0xda24260, v46
	v_div_scale_f32 v51, s[0:1], v50, v50, 1.0
	v_rcp_f32_e32 v52, v51
	v_div_scale_f32 v53, s[2:3], 1.0, v50, 1.0
	v_fma_f32 v48, -v51, v52, 1.0
	v_fmac_f32_e32 v52, v48, v52
	v_mul_f32_e32 v54, v53, v52
	v_fma_f32 v48, -v51, v54, v53
	v_fmac_f32_e32 v54, v48, v52
	v_mov_b64_e32 v[48:49], v[218:219]
	v_mov_b64_e32 v[46:47], v[220:221]
	v_fma_f32 v51, -v51, v54, v53
	s_nop 0
	v_lshlrev_b32_e32 v0, 16, v0
	v_mul_f32_e32 v0, 0xbfb8aa3b, v0
	v_exp_f32_e32 v0, v0
	s_nop 0
	v_lshlrev_b32_e32 v61, 16, v37
	v_lshlrev_b32_e32 v58, 16, v34
	v_and_b32_e32 v34, 0xffff0000, v34
	v_add_f32_e32 v0, 1.0, v0
	v_div_scale_f32 v62, s[0:1], v0, v0, 1.0
	v_rcp_f32_e32 v63, v62
	v_div_scale_f32 v65, vcc, 1.0, v0, 1.0
	v_lshlrev_b32_e32 v59, 16, v35
	v_fma_f32 v66, -v62, v63, 1.0
	v_fmac_f32_e32 v63, v66, v63
	v_mul_f32_e32 v66, v65, v63
	v_fma_f32 v67, -v62, v66, v65
	v_fmac_f32_e32 v66, v67, v63
	v_fma_f32 v62, -v62, v66, v65
	v_div_fmas_f32 v62, v62, v63, v66
	s_mov_b64 vcc, s[2:3]
	v_div_fmas_f32 v51, v51, v52, v54
	v_div_fixup_f32 v0, v62, v0, 1.0
	v_div_fixup_f32 v50, v51, v50, 1.0
	v_mul_f32_e32 v0, v50, v0
	v_fmac_f32_e32 v61, v8, v0
	s_nop 0
	v_and_b32_e32 v8, 0xffff0000, v43
	v_and_b32_e32 v35, 0xffff0000, v35
	v_fmac_f32_e32 v8, v13, v0
	s_nop 0
	v_lshlrev_b32_e32 v13, 16, v46
	v_lshlrev_b32_e32 v53, 16, v38
	v_and_b32_e32 v38, 0xffff0000, v38
	v_lshlrev_b32_e32 v55, 16, v39
	v_and_b32_e32 v39, 0xffff0000, v39
	v_lshlrev_b32_e32 v60, 16, v36
	v_and_b32_e32 v36, 0xffff0000, v36
	v_and_b32_e32 v37, 0xffff0000, v37
	v_fmac_f32_e32 v58, v2, v0
	v_fmac_f32_e32 v34, v3, v0
	v_fmac_f32_e32 v59, v4, v0
	v_fmac_f32_e32 v35, v5, v0
	v_fmac_f32_e32 v13, v14, v0
	v_and_b32_e32 v14, 0xffff0000, v46
	v_cvt_pk_bf16_f32 v232, v58, v34
	v_cvt_pk_bf16_f32 v233, v59, v35
	v_lshlrev_b32_e32 v56, 16, v40
	v_and_b32_e32 v40, 0xffff0000, v40
	v_lshlrev_b32_e32 v57, 16, v41
	v_and_b32_e32 v41, 0xffff0000, v41
	v_lshlrev_b32_e32 v64, 16, v42
	v_fmac_f32_e32 v53, v18, v0
	v_fmac_f32_e32 v38, v19, v0
	v_fmac_f32_e32 v55, v20, v0
	v_fmac_f32_e32 v39, v21, v0
	v_fmac_f32_e32 v60, v6, v0
	v_fmac_f32_e32 v36, v7, v0
	v_fmac_f32_e32 v37, v9, v0
	v_and_b32_e32 v6, 0xffff0000, v42
	v_lshlrev_b32_e32 v7, 16, v43
	v_fmac_f32_e32 v14, v15, v0
	v_lshlrev_b32_e32 v15, 16, v47
	v_cvt_pk_bf16_f32 v240, v53, v38
	v_cvt_pk_bf16_f32 v241, v55, v39
	s_nop 0
	s_nop 0
	v_cvt_pk_bf16_f32 v234, v60, v36
	v_cvt_pk_bf16_f32 v235, v61, v37
	v_fmac_f32_e32 v56, v22, v0
	v_fmac_f32_e32 v40, v23, v0
	v_fmac_f32_e32 v57, v24, v0
	v_fmac_f32_e32 v41, v25, v0
	v_fmac_f32_e32 v64, v10, v0
	v_fmac_f32_e32 v6, v11, v0
	v_fmac_f32_e32 v7, v12, v0
	v_lshlrev_b32_e32 v9, 16, v44
	v_and_b32_e32 v10, 0xffff0000, v44
	v_lshlrev_b32_e32 v11, 16, v45
	v_and_b32_e32 v12, 0xffff0000, v45
	v_fmac_f32_e32 v15, v16, v0
	v_and_b32_e32 v16, 0xffff0000, v47
	v_cvt_pk_bf16_f32 v242, v56, v40
	v_cvt_pk_bf16_f32 v243, v57, v41
	v_and_b32_e32 v248, 32, v200
	v_lshrrev_b32_e32 v248, 2, v248
	v_mov_b32_e32 v249, 0
	v_lshl_add_u64 v[248:249], v[148:149], 0, v[248:249]
	v_permlane32_swap_b32_e32 v232, v234
	v_permlane32_swap_b32_e32 v233, v235
	global_store_dwordx4 v[248:249], v[232:235], off
	s_nop 1
	v_permlane32_swap_b32_e32 v240, v242
	v_permlane32_swap_b32_e32 v241, v243
	global_store_dwordx4 v[248:249], v[240:243], off offset:64
	v_cvt_pk_bf16_f32 v236, v64, v6
	v_cvt_pk_bf16_f32 v237, v7, v8
	v_fmac_f32_e32 v9, v26, v0
	v_fmac_f32_e32 v10, v27, v0
	v_fmac_f32_e32 v11, v28, v0
	v_fmac_f32_e32 v12, v29, v0
	v_fmac_f32_e32 v16, v17, v0
	v_lshlrev_b32_e32 v17, 16, v48
	v_and_b32_e32 v18, 0xffff0000, v48
	v_lshlrev_b32_e32 v19, 16, v49
	v_and_b32_e32 v20, 0xffff0000, v49
	v_cvt_pk_bf16_f32 v244, v9, v10
	v_cvt_pk_bf16_f32 v245, v11, v12
	s_nop 0
	s_nop 0
	v_cvt_pk_bf16_f32 v238, v13, v14
	v_cvt_pk_bf16_f32 v239, v15, v16
	s_mov_b64 s[2:3], 0
	s_and_b64 vcc, exec, s[50:51]
	v_fmac_f32_e32 v17, v30, v0
	v_fmac_f32_e32 v18, v31, v0
	v_fmac_f32_e32 v19, v32, v0
	v_fmac_f32_e32 v20, v33, v0
	v_cvt_pk_bf16_f32 v246, v17, v18
	v_cvt_pk_bf16_f32 v247, v19, v20
	v_permlane32_swap_b32_e32 v236, v238
	v_permlane32_swap_b32_e32 v237, v239
	global_store_dwordx4 v[248:249], v[236:239], off offset:32
	s_nop 1
	v_permlane32_swap_b32_e32 v244, v246
	v_permlane32_swap_b32_e32 v245, v247
	global_store_dwordx4 v[248:249], v[244:247], off offset:96
	s_cbranch_vccnz .LBB0_622

.LBB0_650:
	v_lshl_add_u32 v72, v185, 1, v185
	v_lshl_add_u64 v[66:67], v[152:153], 1, s[14:15]
	v_lshlrev_b64 v[68:69], 11, v[146:147]
	v_ashrrev_i32_e32 v73, 31, v72
	v_lshl_add_u64 v[68:69], v[66:67], 0, v[68:69]
	v_lshlrev_b32_e32 v0, 3, v186
	v_lshl_add_u64 v[72:73], v[72:73], 1, s[12:13]
	v_lshl_add_u64 v[146:147], v[68:69], 0, v[0:1]
	v_lshl_add_u64 v[154:155], v[72:73], 0, v[154:155]
	global_load_dwordx2 v[68:69], v[146:147], off offset:64
	global_load_dwordx2 v[70:71], v[146:147], off offset:80
	global_load_dwordx2 v[74:75], v[146:147], off offset:96
	global_load_ushort v84, v[154:155], off offset:2818
	global_load_dwordx2 v[72:73], v[146:147], off
	global_load_dwordx2 v[76:77], v[146:147], off offset:16
	global_load_dwordx2 v[78:79], v[146:147], off offset:32
	v_add_co_u32_e32 v226, vcc, 0x10000, v146
	s_nop 1
	v_addc_co_u32_e32 v227, vcc, 0, v147, vcc
	v_lshl_add_u64 v[228:229], v[154:155], 0, s[20:21]
	global_load_dwordx2 v[206:207], v[226:227], off offset:64
	global_load_dwordx2 v[208:209], v[226:227], off
	global_load_dwordx2 v[210:211], v[226:227], off offset:16
	global_load_dwordx2 v[212:213], v[226:227], off offset:80
	global_load_dwordx2 v[214:215], v[226:227], off offset:32
	global_load_dwordx2 v[216:217], v[226:227], off offset:96
	global_load_dwordx2 v[218:219], v[226:227], off offset:112
	global_load_dwordx2 v[220:221], v[226:227], off offset:48
	global_load_ushort v224, v[228:229], off offset:2818
	v_and_b32_e32 v81, 64, v174
	v_xor_b32_e32 v80, 32, v174
	v_add_u32_e32 v81, 64, v81
	v_cmp_lt_i32_e32 vcc, v80, v81
	v_lshl_add_u64 v[152:153], v[154:155], 0, s[20:21]
	s_waitcnt vmcnt(3)
	v_lshlrev_b32_e32 v84, 16, v84
	v_cndmask_b32_e32 v80, v174, v80, vcc
	v_lshlrev_b32_e32 v166, 2, v80
	ds_bpermute_b32 v82, v166, v157
	global_load_dwordx2 v[80:81], v[146:147], off offset:48
	v_mul_f32_e32 v84, 0xbfb8aa3b, v84
	v_exp_f32_e32 v84, v84
	s_waitcnt vmcnt(3)
	v_lshlrev_b32_e32 v95, 16, v72
	s_waitcnt lgkmcnt(0)
	v_add_f32_e32 v82, v157, v82
	v_max_f32_e32 v85, 0xda24260, v82
	global_load_dwordx2 v[82:83], v[146:147], off offset:112
	v_add_f32_e32 v84, 1.0, v84
	v_div_scale_f32 v101, s[0:1], v84, v84, 1.0
	v_div_scale_f32 v86, s[0:1], v85, v85, 1.0
	v_rcp_f32_e32 v102, v101
	v_rcp_f32_e32 v87, v86
	v_div_scale_f32 v103, vcc, 1.0, v84, 1.0
	v_fma_f32 v104, -v101, v102, 1.0
	v_fma_f32 v89, -v86, v87, 1.0
	v_fmac_f32_e32 v102, v104, v102
	v_div_scale_f32 v88, s[2:3], 1.0, v85, 1.0
	v_fmac_f32_e32 v87, v89, v87
	v_mul_f32_e32 v104, v103, v102
	v_mul_f32_e32 v89, v88, v87
	v_fma_f32 v105, -v101, v104, v103
	v_fma_f32 v90, -v86, v89, v88
	v_fmac_f32_e32 v104, v105, v102
	v_fmac_f32_e32 v89, v90, v87
	v_fma_f32 v101, -v101, v104, v103
	v_fma_f32 v86, -v86, v89, v88
	v_div_fmas_f32 v101, v101, v102, v104
	s_mov_b64 vcc, s[2:3]
	v_div_fmas_f32 v86, v86, v87, v89
	v_div_fixup_f32 v84, v101, v84, 1.0
	v_div_fixup_f32 v85, v86, v85, 1.0
	v_lshlrev_b32_e32 v88, 16, v68
	v_and_b32_e32 v68, 0xffff0000, v68
	v_and_b32_e32 v72, 0xffff0000, v72
	v_lshlrev_b32_e32 v96, 16, v73
	v_and_b32_e32 v73, 0xffff0000, v73
	v_mul_f32_e32 v84, v85, v84
	v_lshlrev_b32_e32 v90, 16, v69
	v_and_b32_e32 v69, 0xffff0000, v69
	v_lshlrev_b32_e32 v91, 16, v70
	v_and_b32_e32 v70, 0xffff0000, v70
	s_waitcnt vmcnt(3)
	v_lshlrev_b32_e32 v97, 16, v76
	v_and_b32_e32 v76, 0xffff0000, v76
	v_lshlrev_b32_e32 v98, 16, v77
	v_and_b32_e32 v77, 0xffff0000, v77
	v_fmac_f32_e32 v95, v50, v84
	v_fmac_f32_e32 v72, v51, v84
	v_fmac_f32_e32 v96, v52, v84
	v_fmac_f32_e32 v73, v53, v84
	v_fmac_f32_e32 v88, v34, v84
	v_fmac_f32_e32 v68, v35, v84
	v_cvt_pk_bf16_f32 v232, v95, v72
	v_cvt_pk_bf16_f32 v233, v96, v73
	v_lshlrev_b32_e32 v92, 16, v71
	v_and_b32_e32 v71, 0xffff0000, v71
	s_waitcnt vmcnt(2)
	v_lshlrev_b32_e32 v99, 16, v78
	v_and_b32_e32 v78, 0xffff0000, v78
	v_lshlrev_b32_e32 v100, 16, v79
	v_and_b32_e32 v79, 0xffff0000, v79
	v_fmac_f32_e32 v90, v36, v84
	v_fmac_f32_e32 v69, v37, v84
	v_fmac_f32_e32 v97, v54, v84
	v_fmac_f32_e32 v76, v55, v84
	v_fmac_f32_e32 v98, v56, v84
	v_fmac_f32_e32 v77, v57, v84
	v_fmac_f32_e32 v91, v38, v84
	v_fmac_f32_e32 v70, v39, v84
	v_cvt_pk_bf16_f32 v240, v88, v68
	v_cvt_pk_bf16_f32 v241, v90, v69
	s_nop 0
	s_nop 0
	v_cvt_pk_bf16_f32 v234, v97, v76
	v_cvt_pk_bf16_f32 v235, v98, v77
	v_lshlrev_b32_e32 v93, 16, v74
	v_and_b32_e32 v74, 0xffff0000, v74
	v_lshlrev_b32_e32 v94, 16, v75
	v_and_b32_e32 v75, 0xffff0000, v75
	s_waitcnt vmcnt(1)
	v_lshlrev_b32_e32 v38, 16, v80
	v_and_b32_e32 v39, 0xffff0000, v80
	v_fmac_f32_e32 v92, v40, v84
	v_fmac_f32_e32 v71, v41, v84
	v_fmac_f32_e32 v99, v58, v84
	v_fmac_f32_e32 v78, v59, v84
	v_fmac_f32_e32 v100, v60, v84
	v_fmac_f32_e32 v79, v61, v84
	v_fmac_f32_e32 v38, v62, v84
	v_fmac_f32_e32 v39, v63, v84
	v_cvt_pk_bf16_f32 v242, v91, v70
	v_cvt_pk_bf16_f32 v243, v92, v71
	v_and_b32_e32 v248, 32, v200
	v_lshrrev_b32_e32 v248, 2, v248
	v_mov_b32_e32 v249, 0
	v_lshl_add_u64 v[248:249], v[146:147], 0, v[248:249]
	v_permlane32_swap_b32_e32 v232, v234
	v_permlane32_swap_b32_e32 v233, v235
	global_store_dwordx4 v[248:249], v[232:235], off
	s_nop 1
	v_permlane32_swap_b32_e32 v240, v242
	v_permlane32_swap_b32_e32 v241, v243
	global_store_dwordx4 v[248:249], v[240:243], off offset:64
	v_cvt_pk_bf16_f32 v236, v99, v78
	v_cvt_pk_bf16_f32 v237, v100, v79
	v_fmac_f32_e32 v93, v42, v84
	v_fmac_f32_e32 v74, v43, v84
	v_fmac_f32_e32 v94, v44, v84
	v_fmac_f32_e32 v75, v45, v84
	v_cvt_pk_bf16_f32 v244, v93, v74
	v_cvt_pk_bf16_f32 v245, v94, v75
	s_nop 0
	s_nop 0
	v_cvt_pk_bf16_f32 v238, v38, v39
	v_lshlrev_b64 v[38:39], 11, v[148:149]
	v_lshlrev_b32_e32 v40, 16, v81
	v_and_b32_e32 v41, 0xffff0000, v81
	v_lshl_add_u64 v[38:39], v[66:67], 0, v[38:39]
	v_fmac_f32_e32 v40, v64, v84
	v_fmac_f32_e32 v41, v65, v84
	s_waitcnt vmcnt(2)
	v_lshlrev_b32_e32 v42, 16, v82
	v_and_b32_e32 v43, 0xffff0000, v82
	v_lshlrev_b32_e32 v44, 16, v83
	v_and_b32_e32 v45, 0xffff0000, v83
	v_cvt_pk_bf16_f32 v239, v40, v41
	v_lshl_add_u64 v[148:149], v[38:39], 0, v[0:1]
	v_fmac_f32_e32 v42, v46, v84
	v_fmac_f32_e32 v43, v47, v84
	v_fmac_f32_e32 v44, v48, v84
	v_fmac_f32_e32 v45, v49, v84
	v_cvt_pk_bf16_f32 v246, v42, v43
	v_cvt_pk_bf16_f32 v247, v44, v45
	s_waitcnt vmcnt(2)
	v_mov_b64_e32 v[38:39], v[206:207]
	s_nop 0
	v_permlane32_swap_b32_e32 v236, v238
	v_permlane32_swap_b32_e32 v237, v239
	global_store_dwordx4 v[248:249], v[236:239], off offset:32
	v_permlane32_swap_b32_e32 v244, v246
	v_permlane32_swap_b32_e32 v245, v247
	global_store_dwordx4 v[248:249], v[244:247], off offset:96
	v_mov_b32_e32 v0, v224
	s_nop 0
	v_mov_b64_e32 v[34:35], v[208:209]
	v_mov_b64_e32 v[36:37], v[210:211]
	v_mov_b64_e32 v[40:41], v[212:213]
	v_mov_b64_e32 v[42:43], v[214:215]
	ds_bpermute_b32 v46, v166, v156
	v_mov_b64_e32 v[44:45], v[216:217]
	s_waitcnt lgkmcnt(0)
	v_add_f32_e32 v46, v156, v46
	v_max_f32_e32 v50, 0xda24260, v46
	v_div_scale_f32 v51, s[0:1], v50, v50, 1.0
	v_rcp_f32_e32 v52, v51
	v_div_scale_f32 v53, s[2:3], 1.0, v50, 1.0
	v_fma_f32 v48, -v51, v52, 1.0
	v_fmac_f32_e32 v52, v48, v52
	v_mul_f32_e32 v54, v53, v52
	v_fma_f32 v48, -v51, v54, v53
	v_fmac_f32_e32 v54, v48, v52
	v_mov_b64_e32 v[48:49], v[218:219]
	v_mov_b64_e32 v[46:47], v[220:221]
	v_fma_f32 v51, -v51, v54, v53
	s_nop 0
	v_lshlrev_b32_e32 v0, 16, v0
	v_mul_f32_e32 v0, 0xbfb8aa3b, v0
	v_exp_f32_e32 v0, v0
	v_lshlrev_b32_e32 v55, 16, v39
	v_and_b32_e32 v39, 0xffff0000, v39
	s_nop 0
	v_lshlrev_b32_e32 v60, 16, v36
	v_add_f32_e32 v0, 1.0, v0
	v_div_scale_f32 v58, s[0:1], v0, v0, 1.0
	v_rcp_f32_e32 v59, v58
	v_div_scale_f32 v61, vcc, 1.0, v0, 1.0
	v_lshlrev_b32_e32 v53, 16, v38
	v_fma_f32 v62, -v58, v59, 1.0
	v_fmac_f32_e32 v59, v62, v59
	v_mul_f32_e32 v62, v61, v59
	v_fma_f32 v63, -v58, v62, v61
	v_fmac_f32_e32 v62, v63, v59
	v_fma_f32 v58, -v58, v62, v61
	v_div_fmas_f32 v58, v58, v59, v62
	s_mov_b64 vcc, s[2:3]
	v_div_fmas_f32 v51, v51, v52, v54
	v_div_fixup_f32 v0, v58, v0, 1.0
	v_div_fixup_f32 v50, v51, v50, 1.0
	v_mul_f32_e32 v0, v50, v0
	v_fmac_f32_e32 v55, v20, v0
	v_fmac_f32_e32 v39, v21, v0
	v_fmac_f32_e32 v60, v6, v0
	v_and_b32_e32 v6, 0xffff0000, v36
	s_nop 0
	v_and_b32_e32 v20, 0xffff0000, v41
	s_nop 0
	v_lshlrev_b32_e32 v21, 16, v42
	v_fmac_f32_e32 v6, v7, v0
	v_lshlrev_b32_e32 v7, 16, v37
	v_fmac_f32_e32 v20, v25, v0
	v_fmac_f32_e32 v21, v10, v0
	v_and_b32_e32 v10, 0xffff0000, v42
	s_nop 0
	v_lshlrev_b32_e32 v25, 16, v46
	v_and_b32_e32 v38, 0xffff0000, v38
	v_lshlrev_b32_e32 v56, 16, v34
	v_and_b32_e32 v34, 0xffff0000, v34
	v_lshlrev_b32_e32 v57, 16, v35
	v_and_b32_e32 v35, 0xffff0000, v35
	v_fmac_f32_e32 v7, v8, v0
	v_and_b32_e32 v8, 0xffff0000, v37
	v_fmac_f32_e32 v10, v11, v0
	v_lshlrev_b32_e32 v11, 16, v43
	v_fmac_f32_e32 v25, v14, v0
	v_and_b32_e32 v14, 0xffff0000, v46
	s_add_i32 s0, s84, -8
	v_fmac_f32_e32 v56, v2, v0
	v_fmac_f32_e32 v34, v3, v0
	v_fmac_f32_e32 v57, v4, v0
	v_fmac_f32_e32 v35, v5, v0
	v_fmac_f32_e32 v53, v18, v0
	v_fmac_f32_e32 v38, v19, v0
	v_fmac_f32_e32 v8, v9, v0
	v_lshlrev_b32_e32 v9, 16, v40
	v_and_b32_e32 v18, 0xffff0000, v40
	v_lshlrev_b32_e32 v19, 16, v41
	v_fmac_f32_e32 v11, v12, v0
	v_and_b32_e32 v12, 0xffff0000, v43
	v_fmac_f32_e32 v14, v15, v0
	v_lshlrev_b32_e32 v15, 16, v47
	v_cvt_pk_bf16_f32 v232, v56, v34
	v_cvt_pk_bf16_f32 v233, v57, v35
	v_cvt_pk_bf16_f32 v240, v53, v38
	v_cvt_pk_bf16_f32 v241, v55, v39
	s_cmp_gt_u32 s61, 1
	v_fmac_f32_e32 v9, v22, v0
	v_fmac_f32_e32 v18, v23, v0
	v_fmac_f32_e32 v19, v24, v0
	v_fmac_f32_e32 v12, v13, v0
	v_lshlrev_b32_e32 v13, 16, v44
	v_and_b32_e32 v22, 0xffff0000, v44
	v_lshlrev_b32_e32 v23, 16, v45
	v_and_b32_e32 v24, 0xffff0000, v45
	v_fmac_f32_e32 v15, v16, v0
	v_and_b32_e32 v16, 0xffff0000, v47
	s_nop 0
	s_nop 0
	v_cvt_pk_bf16_f32 v234, v60, v6
	v_cvt_pk_bf16_f32 v235, v7, v8
	v_cvt_pk_bf16_f32 v242, v9, v18
	v_cvt_pk_bf16_f32 v243, v19, v20
	s_cselect_b32 s85, s0, 0
	v_fmac_f32_e32 v13, v26, v0
	v_fmac_f32_e32 v22, v27, v0
	v_fmac_f32_e32 v23, v28, v0
	v_fmac_f32_e32 v24, v29, v0
	v_fmac_f32_e32 v16, v17, v0
	v_lshlrev_b32_e32 v17, 16, v48
	v_and_b32_e32 v26, 0xffff0000, v48
	v_lshlrev_b32_e32 v27, 16, v49
	v_and_b32_e32 v28, 0xffff0000, v49
	v_and_b32_e32 v248, 32, v200
	v_lshrrev_b32_e32 v248, 2, v248
	v_mov_b32_e32 v249, 0
	v_lshl_add_u64 v[248:249], v[148:149], 0, v[248:249]
	v_permlane32_swap_b32_e32 v232, v234
	v_permlane32_swap_b32_e32 v233, v235
	global_store_dwordx4 v[248:249], v[232:235], off
	v_permlane32_swap_b32_e32 v240, v242
	v_permlane32_swap_b32_e32 v241, v243
	global_store_dwordx4 v[248:249], v[240:243], off offset:64
	v_cvt_pk_bf16_f32 v236, v21, v10
	v_cvt_pk_bf16_f32 v237, v11, v12
	v_cvt_pk_bf16_f32 v244, v13, v22
	v_cvt_pk_bf16_f32 v245, v23, v24
	s_cmp_gt_u32 s85, s84
	v_fmac_f32_e32 v17, v30, v0
	v_fmac_f32_e32 v26, v31, v0
	v_fmac_f32_e32 v27, v32, v0
	v_fmac_f32_e32 v28, v33, v0
	s_nop 0
	s_nop 0
	v_cvt_pk_bf16_f32 v238, v25, v14
	v_cvt_pk_bf16_f32 v239, v15, v16
	v_cvt_pk_bf16_f32 v246, v17, v26
	v_cvt_pk_bf16_f32 v247, v27, v28
	v_permlane32_swap_b32_e32 v236, v238
	v_permlane32_swap_b32_e32 v237, v239
	global_store_dwordx4 v[248:249], v[236:239], off offset:32
	s_nop 1
	v_permlane32_swap_b32_e32 v244, v246
	v_permlane32_swap_b32_e32 v245, v247
	global_store_dwordx4 v[248:249], v[244:247], off offset:96
	s_cbranch_scc1 .LBB0_624
	s_lshl_b32 s84, s85, 6
	v_add_u32_e32 v0, s84, v183
	v_med3_i32 v0, v0, 0, v141
	v_mul_u32_u24_e32 v0, 0x600, v0
	v_lshl_add_u64 v[2:3], v[0:1], 1, s[44:45]
	v_lshlrev_b32_e32 v0, 1, v150
	v_lshl_add_u64 v[2:3], v[2:3], 0, v[0:1]
	global_load_dwordx4 v[18:21], v[2:3], off offset:2048
	global_load_dwordx4 v[22:25], v[2:3], off offset:2176
	s_add_i32 s60, s60, -11
	v_add3_u32 v0, s60, v181, v151
	v_sub_u32_e32 v0, v0, v184
	s_barrier
	v_mov_b32_e32 v16, v1
	v_mov_b32_e32 v17, v1
	v_mov_b32_e32 v2, v1
	v_mov_b32_e32 v3, v1
	v_mov_b32_e32 v4, v1
	v_mov_b32_e32 v5, v1
	v_mov_b32_e32 v6, v1
	v_mov_b32_e32 v7, v1
	v_mov_b32_e32 v8, v1
	v_mov_b32_e32 v9, v1
	v_mov_b32_e32 v10, v1
	v_mov_b32_e32 v11, v1
	v_mov_b32_e32 v12, v1
	v_mov_b32_e32 v13, v1
	v_mov_b32_e32 v14, v1
	v_mov_b32_e32 v15, v1
	v_subrev_u32_e32 v181, s84, v0
	v_mov_b32_e32 v0, v1
	v_mov_b64_e32 v[48:49], v[16:17]
	v_mov_b64_e32 v[64:65], v[16:17]
	s_mov_b32 s86, 0
	v_add_u32_e32 v167, 0xffffff80, v182
	v_add_u32_e32 v168, 0xfffffe01, v182
	v_add_u32_e32 v169, 0xfffffe21, v182
	v_add_u32_e32 v183, 0xfffffe40, v182
	v_add_u32_e32 v185, 0xfffffe20, v182
	v_add_u32_e32 v182, 0xffffffa0, v182
	v_mov_b32_e32 v186, 0xf149f2ca
	v_mov_b64_e32 v[46:47], v[14:15]
	v_mov_b64_e32 v[44:45], v[12:13]
	v_mov_b64_e32 v[42:43], v[10:11]
	v_mov_b64_e32 v[40:41], v[8:9]
	v_mov_b64_e32 v[38:39], v[6:7]
	v_mov_b64_e32 v[36:37], v[4:5]
	v_mov_b64_e32 v[34:35], v[2:3]
	v_mov_b64_e32 v[62:63], v[14:15]
	v_mov_b64_e32 v[60:61], v[12:13]
	v_mov_b64_e32 v[58:59], v[10:11]
	v_mov_b64_e32 v[56:57], v[8:9]
	v_mov_b64_e32 v[54:55], v[6:7]
	v_mov_b64_e32 v[52:53], v[4:5]
	v_mov_b64_e32 v[50:51], v[2:3]
	v_mov_b32_e32 v187, 0xf149f2ca
	v_mov_b64_e32 v[150:151], v[0:1]
	s_waitcnt vmcnt(1)
	ds_write_b128 v140, v[18:21]
	s_waitcnt vmcnt(0)
	ds_write_b128 v142, v[22:25] offset:18432
	s_waitcnt lgkmcnt(0)
	s_barrier
	ds_read_b32 v184, v175 offset:43524
	v_mov_b64_e32 v[32:33], v[16:17]
	v_mov_b64_e32 v[30:31], v[14:15]
	v_mov_b64_e32 v[28:29], v[12:13]
	v_mov_b64_e32 v[26:27], v[10:11]
	v_mov_b64_e32 v[24:25], v[8:9]
	v_mov_b64_e32 v[22:23], v[6:7]
	v_mov_b64_e32 v[20:21], v[4:5]
	v_mov_b64_e32 v[18:19], v[2:3]
	s_branch .LBB0_653

.LBB0_1285:
	ds_bpermute_b32 v64, v204, v179
	v_mov_b32_e32 v175, v169
	s_mov_b64 s[2:3], 0
	s_waitcnt lgkmcnt(0)
	v_add_f32_e32 v64, v179, v64
	v_max_f32_e32 v64, 0xda24260, v64
	v_div_scale_f32 v65, s[0:1], v64, v64, 1.0
	v_rcp_f32_e32 v66, v65
	v_div_scale_f32 v67, vcc, 1.0, v64, 1.0
	v_fma_f32 v68, -v65, v66, 1.0
	v_fmac_f32_e32 v66, v68, v66
	v_mul_f32_e32 v68, v67, v66
	v_fma_f32 v69, -v65, v68, v67
	v_fmac_f32_e32 v68, v69, v66
	v_fma_f32 v65, -v65, v68, v67
	v_div_fmas_f32 v65, v65, v66, v68
	v_div_fixup_f32 v64, v65, v64, 1.0
	v_mul_f32_e32 v65, v32, v64
	v_mul_f32_e32 v66, v33, v64
	v_lshlrev_b64 v[32:33], 11, v[172:173]
	v_lshl_add_u64 v[32:33], s[70:71], 0, v[32:33]
	v_mul_f32_e32 v48, v48, v64
	v_mul_f32_e32 v49, v49, v64
	v_mul_f32_e32 v50, v50, v64
	v_mul_f32_e32 v67, v34, v64
	v_mul_f32_e32 v51, v51, v64
	v_mul_f32_e32 v68, v35, v64
	v_mul_f32_e32 v69, v36, v64
	v_mul_f32_e32 v70, v37, v64
	v_mul_f32_e32 v38, v38, v64
	v_lshl_add_u64 v[32:33], v[32:33], 0, v[174:175]
	v_cvt_pk_bf16_f32 v232, v48, v49
	v_cvt_pk_bf16_f32 v233, v50, v51
	v_cvt_pk_bf16_f32 v240, v65, v66
	v_cvt_pk_bf16_f32 v241, v67, v68
	v_mul_f32_e32 v52, v52, v64
	v_mul_f32_e32 v53, v53, v64
	v_mul_f32_e32 v54, v54, v64
	v_mul_f32_e32 v55, v55, v64
	v_mul_f32_e32 v39, v39, v64
	s_nop 0
	s_nop 0
	v_cvt_pk_bf16_f32 v234, v52, v53
	v_cvt_pk_bf16_f32 v235, v54, v55
	v_cvt_pk_bf16_f32 v242, v69, v70
	v_cvt_pk_bf16_f32 v243, v38, v39
	ds_bpermute_b32 v38, v204, v178
	v_mul_f32_e32 v56, v56, v64
	v_mul_f32_e32 v40, v40, v64
	v_mul_f32_e32 v57, v57, v64
	v_mul_f32_e32 v41, v41, v64
	v_mul_f32_e32 v58, v58, v64
	v_mul_f32_e32 v42, v42, v64
	v_mul_f32_e32 v59, v59, v64
	v_mul_f32_e32 v43, v43, v64
	v_and_b32_e32 v248, 32, v200
	v_lshrrev_b32_e32 v248, 2, v248
	v_mov_b32_e32 v249, 0
	v_lshl_add_u64 v[248:249], v[32:33], 0, v[248:249]
	v_permlane32_swap_b32_e32 v232, v234
	v_permlane32_swap_b32_e32 v233, v235
	global_store_dwordx4 v[248:249], v[232:235], off
	v_permlane32_swap_b32_e32 v240, v242
	v_permlane32_swap_b32_e32 v241, v243
	global_store_dwordx4 v[248:249], v[240:243], off offset:64
	v_cvt_pk_bf16_f32 v236, v56, v57
	v_cvt_pk_bf16_f32 v237, v58, v59
	v_cvt_pk_bf16_f32 v244, v40, v41
	v_cvt_pk_bf16_f32 v245, v42, v43
	s_nop 0
	s_waitcnt lgkmcnt(0)
	v_add_f32_e32 v37, v178, v38
	v_max_f32_e32 v38, 0xda24260, v37
	v_div_scale_f32 v39, s[0:1], v38, v38, 1.0
	v_rcp_f32_e32 v40, v39
	v_mul_f32_e32 v60, v60, v64
	v_mul_f32_e32 v61, v61, v64
	v_mul_f32_e32 v62, v62, v64
	v_mul_f32_e32 v63, v63, v64
	s_nop 0
	v_cvt_pk_bf16_f32 v238, v60, v61
	v_cvt_pk_bf16_f32 v239, v62, v63
	v_mul_f32_e32 v44, v44, v64
	v_mul_f32_e32 v45, v45, v64
	v_mul_f32_e32 v46, v46, v64
	v_mul_f32_e32 v47, v47, v64
	v_cvt_pk_bf16_f32 v246, v44, v45
	v_cvt_pk_bf16_f32 v247, v46, v47
	v_permlane32_swap_b32_e32 v236, v238
	v_permlane32_swap_b32_e32 v237, v239
	global_store_dwordx4 v[248:249], v[236:239], off offset:32
	s_nop 1
	v_permlane32_swap_b32_e32 v244, v246
	v_permlane32_swap_b32_e32 v245, v247
	global_store_dwordx4 v[248:249], v[244:247], off offset:96
	v_fma_f32 v32, -v39, v40, 1.0
	v_fmac_f32_e32 v40, v32, v40
	v_div_scale_f32 v32, vcc, 1.0, v38, 1.0
	v_mul_f32_e32 v33, v32, v40
	v_fma_f32 v34, -v39, v33, v32
	v_fmac_f32_e32 v33, v34, v40
	v_fma_f32 v32, -v39, v33, v32
	v_div_fmas_f32 v32, v32, v40, v33
	v_div_fixup_f32 v32, v32, v38, 1.0
	v_mul_f32_e32 v33, v0, v32
	v_mul_f32_e32 v34, v1, v32
	v_lshlrev_b64 v[0:1], 11, v[176:177]
	v_mul_f32_e32 v3, v3, v32
	v_lshl_add_u64 v[0:1], s[70:71], 0, v[0:1]
	v_mul_f32_e32 v35, v2, v32
	v_lshl_add_u64 v[0:1], v[0:1], 0, v[174:175]
	v_cvt_pk_bf16_f32 v232, v33, v34
	v_cvt_pk_bf16_f32 v233, v35, v3
	v_mul_f32_e32 v16, v16, v32
	v_mul_f32_e32 v17, v17, v32
	v_mul_f32_e32 v18, v18, v32
	v_mul_f32_e32 v19, v19, v32
	v_mul_f32_e32 v36, v4, v32
	v_mul_f32_e32 v37, v5, v32
	v_mul_f32_e32 v6, v6, v32
	v_mul_f32_e32 v7, v7, v32
	v_cvt_pk_bf16_f32 v240, v16, v17
	v_cvt_pk_bf16_f32 v241, v18, v19
	s_nop 0
	s_nop 0
	v_cvt_pk_bf16_f32 v234, v36, v37
	v_cvt_pk_bf16_f32 v235, v6, v7
	v_mul_f32_e32 v20, v20, v32
	v_mul_f32_e32 v21, v21, v32
	v_mul_f32_e32 v22, v22, v32
	v_mul_f32_e32 v23, v23, v32
	v_mul_f32_e32 v8, v8, v32
	v_mul_f32_e32 v9, v9, v32
	v_mul_f32_e32 v10, v10, v32
	v_mul_f32_e32 v11, v11, v32
	v_cvt_pk_bf16_f32 v242, v20, v21
	v_cvt_pk_bf16_f32 v243, v22, v23
	v_and_b32_e32 v248, 32, v200
	v_lshrrev_b32_e32 v248, 2, v248
	v_mov_b32_e32 v249, 0
	v_lshl_add_u64 v[248:249], v[0:1], 0, v[248:249]
	v_permlane32_swap_b32_e32 v232, v234
	v_permlane32_swap_b32_e32 v233, v235
	global_store_dwordx4 v[248:249], v[232:235], off
	s_nop 1
	v_permlane32_swap_b32_e32 v240, v242
	v_permlane32_swap_b32_e32 v241, v243
	global_store_dwordx4 v[248:249], v[240:243], off offset:64
	v_cvt_pk_bf16_f32 v236, v8, v9
	v_cvt_pk_bf16_f32 v237, v10, v11
	v_mul_f32_e32 v24, v24, v32
	v_mul_f32_e32 v25, v25, v32
	v_mul_f32_e32 v26, v26, v32
	v_mul_f32_e32 v27, v27, v32
	v_mul_f32_e32 v12, v12, v32
	v_mul_f32_e32 v13, v13, v32
	v_mul_f32_e32 v14, v14, v32
	v_mul_f32_e32 v15, v15, v32
	v_cvt_pk_bf16_f32 v244, v24, v25
	v_cvt_pk_bf16_f32 v245, v26, v27
	s_nop 0
	s_nop 0
	v_cvt_pk_bf16_f32 v238, v12, v13
	v_cvt_pk_bf16_f32 v239, v14, v15
	s_and_b64 vcc, exec, s[72:73]
	v_mul_f32_e32 v28, v28, v32
	v_mul_f32_e32 v29, v29, v32
	v_mul_f32_e32 v30, v30, v32
	v_mul_f32_e32 v31, v31, v32
	v_cvt_pk_bf16_f32 v246, v28, v29
	v_cvt_pk_bf16_f32 v247, v30, v31
	v_permlane32_swap_b32_e32 v236, v238
	v_permlane32_swap_b32_e32 v237, v239
	global_store_dwordx4 v[248:249], v[236:239], off offset:32
	s_nop 1
	v_permlane32_swap_b32_e32 v244, v246
	v_permlane32_swap_b32_e32 v245, v247
	global_store_dwordx4 v[248:249], v[244:247], off offset:96
	s_cbranch_vccnz .LBB0_1283

.LBB0_1344:
	v_fma_f32 v64, v64, s18, -v197
	v_exp_f32_e32 v131, v64
	v_fma_f32 v64, v113, s18, -v170
	v_fma_f32 v96, v96, s18, -v197
	v_exp_f32_e32 v113, v64
	v_fma_f32 v64, v97, s18, -v197
	v_fma_f32 v112, v112, s18, -v170
	v_exp_f32_e32 v130, v96
	v_exp_f32_e32 v96, v64
	v_fma_f32 v64, v81, s18, -v170
	v_fma_f32 v66, v66, s18, -v197
	v_exp_f32_e32 v129, v112
	v_exp_f32_e32 v112, v64
	v_fma_f32 v64, v65, s18, -v197
	v_exp_f32_e32 v133, v66
	v_fma_f32 v66, v115, s18, -v170
	v_exp_f32_e32 v97, v64
	v_fma_f32 v64, v114, s18, -v170
	v_exp_f32_e32 v81, v66
	v_fma_f32 v66, v99, s18, -v197
	v_fma_f32 v80, v80, s18, -v170
	v_exp_f32_e32 v65, v64
	v_fma_f32 v64, v98, s18, -v197
	v_exp_f32_e32 v98, v66
	v_fma_f32 v66, v83, s18, -v170
	v_fma_f32 v68, v68, s18, -v197
	v_exp_f32_e32 v128, v80
	v_exp_f32_e32 v80, v66
	v_fma_f32 v66, v67, s18, -v197
	v_exp_f32_e32 v115, v68
	v_fma_f32 v68, v117, s18, -v170
	v_exp_f32_e32 v99, v66
	v_fma_f32 v66, v116, s18, -v170
	v_exp_f32_e32 v83, v68
	v_fma_f32 v68, v101, s18, -v197
	v_exp_f32_e32 v67, v66
	v_fma_f32 v66, v100, s18, -v197
	v_exp_f32_e32 v100, v68
	v_fma_f32 v68, v85, s18, -v170
	v_exp_f32_e32 v132, v64
	v_fma_f32 v64, v82, s18, -v170
	v_exp_f32_e32 v82, v68
	v_fma_f32 v68, v69, s18, -v197
	v_exp_f32_e32 v114, v66
	v_fma_f32 v66, v84, s18, -v170
	v_exp_f32_e32 v101, v68
	v_fma_f32 v68, v118, s18, -v170
	v_fma_f32 v84, v119, s18, -v170
	v_exp_f32_e32 v69, v68
	v_fma_f32 v68, v102, s18, -v197
	v_exp_f32_e32 v85, v84
	v_fma_f32 v84, v103, s18, -v197
	v_exp_f32_e32 v116, v68
	v_fma_f32 v68, v86, s18, -v170
	v_exp_f32_e32 v86, v84
	v_fma_f32 v84, v120, s18, -v170
	v_exp_f32_e32 v103, v84
	v_fma_f32 v84, v104, s18, -v197
	v_exp_f32_e32 v120, v84
	v_fma_f32 v84, v121, s18, -v170
	v_exp_f32_e32 v119, v84
	v_fma_f32 v84, v105, s18, -v197
	v_exp_f32_e32 v134, v84
	v_fma_f32 v84, v122, s18, -v170
	v_exp_f32_e32 v105, v84
	v_fma_f32 v84, v106, s18, -v197
	v_exp_f32_e32 v106, v84
	v_fma_f32 v84, v123, s18, -v170
	v_exp_f32_e32 v153, v84
	v_fma_f32 v84, v107, s18, -v197
	v_cvt_pk_bf16_f32 v136, v129, v113
	v_cvt_pk_bf16_f32 v137, v65, v81
	v_cvt_pk_bf16_f32 v138, v67, v83
	v_cvt_pk_bf16_f32 v139, v69, v85
	v_cvt_pk_bf16_f32 v140, v130, v96
	v_cvt_pk_bf16_f32 v141, v132, v98
	v_cvt_pk_bf16_f32 v142, v114, v100
	v_cvt_pk_bf16_f32 v143, v116, v86
	ds_read_b64_tr_b16 v[144:145], v179 offset:30720
	ds_read_b64_tr_b16 v[146:147], v179 offset:32256
	v_exp_f32_e32 v154, v84
	v_fma_f32 v84, v124, s18, -v170
	v_exp_f32_e32 v157, v84
	v_fma_f32 v84, v108, s18, -v197
	v_exp_f32_e32 v158, v84
	v_fma_f32 v84, v125, s18, -v170
	v_exp_f32_e32 v161, v84
	v_fma_f32 v84, v109, s18, -v197
	v_exp_f32_e32 v162, v84
	v_fma_f32 v84, v126, s18, -v170
	s_waitcnt lgkmcnt(0)
	v_mfma_f32_32x32x16_bf16 v[48:63], v[144:147], v[136:139], v[48:63]
	v_fma_f32 v70, v70, s18, -v197
	v_exp_f32_e32 v117, v70
	v_fma_f32 v70, v87, s18, -v170
	ds_read_b64_tr_b16 v[150:151], v179 offset:32320
	ds_read_b64_tr_b16 v[148:149], v179 offset:30784
	v_exp_f32_e32 v64, v64
	v_exp_f32_e32 v66, v66
	v_exp_f32_e32 v68, v68
	v_mfma_f32_32x32x16_bf16 v[0:15], v[144:147], v[140:143], v[0:15]
	v_exp_f32_e32 v145, v84
	v_fma_f32 v84, v110, s18, -v197
	v_exp_f32_e32 v126, v84
	v_fma_f32 v84, v127, s18, -v170
	v_exp_f32_e32 v147, v84
	v_fma_f32 v84, v111, s18, -v197
	v_exp_f32_e32 v164, v84
	v_exp_f32_e32 v84, v70
	v_fma_f32 v70, v71, s18, -v197
	v_exp_f32_e32 v87, v70
	v_fma_f32 v70, v88, s18, -v170
	v_exp_f32_e32 v102, v70
	v_fma_f32 v70, v72, s18, -v197
	v_exp_f32_e32 v121, v70
	v_fma_f32 v70, v89, s18, -v170
	v_exp_f32_e32 v118, v70
	v_fma_f32 v70, v73, s18, -v197
	v_exp_f32_e32 v135, v70
	v_fma_f32 v70, v90, s18, -v170
	v_exp_f32_e32 v104, v70
	v_fma_f32 v70, v74, s18, -v197
	v_fma_f32 v74, v91, s18, -v170
	v_exp_f32_e32 v152, v74
	v_fma_f32 v74, v75, s18, -v197
	v_exp_f32_e32 v155, v74
	v_fma_f32 v74, v92, s18, -v170
	v_exp_f32_e32 v156, v74
	v_fma_f32 v74, v76, s18, -v197
	v_exp_f32_e32 v159, v74
	v_fma_f32 v74, v93, s18, -v170
	v_exp_f32_e32 v160, v74
	v_fma_f32 v74, v77, s18, -v197
	v_exp_f32_e32 v163, v74
	v_fma_f32 v74, v94, s18, -v170
	v_exp_f32_e32 v144, v74
	v_fma_f32 v74, v78, s18, -v197
	v_exp_f32_e32 v127, v74
	v_fma_f32 v74, v95, s18, -v170
	v_exp_f32_e32 v146, v74
	v_fma_f32 v74, v79, s18, -v197
	v_pk_add_f32 v[78:79], v[130:131], 0 op_sel_hi:[1,0]
	s_waitcnt lgkmcnt(0)
	v_mfma_f32_32x32x16_bf16 v[32:47], v[148:151], v[136:139], v[32:47]
	v_add_f32_e64 v78, v96, v78
	v_add_f32_e64 v79, v97, v79
	v_cvt_pk_bf16_f32 v108, v103, v119
	v_cvt_pk_bf16_f32 v109, v105, v153
	v_cvt_pk_bf16_f32 v110, v157, v161
	v_cvt_pk_bf16_f32 v111, v145, v147
	v_cvt_pk_bf16_f32 v122, v120, v134
	v_add_f32_e64 v78, v132, v78
	v_add_f32_e64 v79, v133, v79
	v_cvt_pk_bf16_f32 v123, v106, v154
	v_cvt_pk_bf16_f32 v124, v158, v162
	v_cvt_pk_bf16_f32 v125, v126, v164
	ds_read_b64_tr_b16 v[136:137], v179 offset:33792
	ds_read_b64_tr_b16 v[138:139], v179 offset:35328
	v_pk_add_f32 v[78:79], v[98:99], v[78:79]
	v_mfma_f32_32x32x16_bf16 v[16:31], v[148:151], v[140:143], v[16:31]
	v_add_f32_e64 v78, v114, v78
	v_add_f32_e64 v79, v115, v79
	ds_read_b64_tr_b16 v[142:143], v179 offset:35392
	ds_read_b64_tr_b16 v[140:141], v179 offset:33856
	v_add_f32_e64 v78, v100, v78
	v_add_f32_e64 v79, v101, v79
	v_exp_f32_e32 v107, v70
	v_pk_add_f32 v[78:79], v[116:117], v[78:79]
	v_cvt_pk_bf16_f32 v70, v128, v112
	v_cvt_pk_bf16_f32 v71, v64, v80
	v_cvt_pk_bf16_f32 v72, v66, v82
	v_cvt_pk_bf16_f32 v73, v68, v84
	v_cvt_pk_bf16_f32 v88, v131, v97
	v_cvt_pk_bf16_f32 v89, v133, v99
	v_cvt_pk_bf16_f32 v90, v115, v101
	v_cvt_pk_bf16_f32 v91, v117, v87
	s_nop 0
	v_pk_add_f32 v[78:79], v[86:87], v[78:79]
	v_pk_add_f32 v[86:87], v[128:129], 0 op_sel_hi:[1,0]
	s_waitcnt lgkmcnt(0)
	v_mfma_f32_32x32x16_bf16 v[32:47], v[140:143], v[108:111], v[32:47]
	v_add_f32_e64 v86, v112, v86
	v_add_f32_e64 v87, v113, v87
	v_add_f32_e64 v78, v120, v78
	v_add_f32_e64 v79, v121, v79
	v_add_f32_e64 v64, v64, v86
	v_add_f32_e64 v65, v65, v87
	v_pk_add_f32 v[78:79], v[134:135], v[78:79]
	v_pk_add_f32 v[64:65], v[80:81], v[64:65]
	v_pk_add_f32 v[78:79], v[106:107], v[78:79]
	v_pk_add_f32 v[64:65], v[66:67], v[64:65]
	v_mfma_f32_32x32x16_bf16 v[48:63], v[136:139], v[108:111], v[48:63]
	v_add_f32_e64 v64, v82, v64
	v_add_f32_e64 v65, v83, v65
	ds_read_b64_tr_b16 v[108:109], v179 offset:36864
	ds_read_b64_tr_b16 v[110:111], v179 offset:38400
	v_add_f32_e64 v64, v68, v64
	v_add_f32_e64 v65, v69, v65
	v_exp_f32_e32 v165, v74
	v_pk_add_f32 v[64:65], v[84:85], v[64:65]
	v_pk_add_f32 v[78:79], v[154:155], v[78:79]
	v_pk_add_f32 v[64:65], v[102:103], v[64:65]
	v_mfma_f32_32x32x16_bf16 v[0:15], v[136:139], v[122:125], v[0:15]
	v_add_f32_e64 v64, v118, v64
	v_add_f32_e64 v65, v119, v65
	v_add_f32_e64 v78, v158, v78
	v_add_f32_e64 v79, v159, v79
	v_add_f32_e64 v64, v104, v64
	v_add_f32_e64 v65, v105, v65
	v_pk_add_f32 v[78:79], v[162:163], v[78:79]
	v_pk_add_f32 v[64:65], v[152:153], v[64:65]
	v_pk_add_f32 v[78:79], v[126:127], v[78:79]
	v_pk_add_f32 v[64:65], v[156:157], v[64:65]
	v_mfma_f32_32x32x16_bf16 v[16:31], v[140:143], v[122:125], v[16:31]
	v_add_f32_e64 v64, v160, v64
	v_add_f32_e64 v65, v161, v65
	ds_read_b64_tr_b16 v[124:125], v179 offset:38464
	ds_read_b64_tr_b16 v[122:123], v179 offset:36928
	v_add_f32_e64 v64, v144, v64
	v_add_f32_e64 v65, v145, v65
	s_lshl_b32 s6, s20, 1
	v_pk_add_f32 v[64:65], v[146:147], v[64:65]
	v_lshlrev_b32_e32 v170, 3, v195
	v_add_f32_e32 v64, v64, v65
	v_add_f32_e32 v66, v175, v64
	ds_bpermute_b32 v67, v196, v66
	s_waitcnt lgkmcnt(1)
	v_mfma_f32_32x32x16_bf16 v[32:47], v[122:125], v[70:73], v[32:47]
	v_add_f32_e64 v64, v164, v78
	v_add_f32_e64 v65, v165, v79
	s_add_i32 s17, s17, s30
	v_add_f32_e32 v64, v64, v65
	s_waitcnt lgkmcnt(0)
	v_add_f32_e32 v65, v66, v67
	v_max_f32_e32 v65, 0xda24260, v65
	v_div_scale_f32 v66, s[0:1], v65, v65, 1.0
	v_mfma_f32_32x32x16_bf16 v[48:63], v[108:111], v[70:73], v[48:63]
	v_cvt_pk_bf16_f32 v70, v102, v118
	v_cvt_pk_bf16_f32 v71, v104, v152
	v_cvt_pk_bf16_f32 v72, v156, v160
	v_cvt_pk_bf16_f32 v73, v144, v146
	v_cvt_pk_bf16_f32 v74, v121, v135
	v_cvt_pk_bf16_f32 v75, v107, v155
	v_cvt_pk_bf16_f32 v76, v159, v163
	v_mfma_f32_32x32x16_bf16 v[0:15], v[108:111], v[88:91], v[0:15]
	v_cvt_pk_bf16_f32 v77, v127, v165
	ds_read_b64_tr_b16 v[92:93], v179 offset:39936
	ds_read_b64_tr_b16 v[94:95], v179 offset:41472
	v_rcp_f32_e32 v67, v66
	v_add_f32_e32 v64, v174, v64
	s_cmpk_lt_i32 s17, 0x200
	v_fma_f32 v68, -v66, v67, 1.0
	v_mfma_f32_32x32x16_bf16 v[16:31], v[122:125], v[88:91], v[16:31]
	ds_read_b64_tr_b16 v[90:91], v179 offset:41536
	ds_read_b64_tr_b16 v[88:89], v179 offset:40000
	v_fmac_f32_e32 v67, v68, v67
	v_div_scale_f32 v68, vcc, 1.0, v65, 1.0
	v_mul_f32_e32 v69, v68, v67
	s_waitcnt lgkmcnt(0)
	s_barrier
	v_mfma_f32_32x32x16_bf16 v[32:47], v[88:91], v[70:73], v[32:47]
	v_mfma_f32_32x32x16_bf16 v[48:63], v[92:95], v[70:73], v[48:63]
	v_fma_f32 v70, -v66, v69, v68
	v_fmac_f32_e32 v69, v70, v67
	v_fma_f32 v66, -v66, v69, v68
	v_div_fmas_f32 v66, v66, v67, v69
	v_div_fixup_f32 v65, v66, v65, 1.0
	s_nop 5
	v_mul_f32_e32 v66, v32, v65
	v_mul_f32_e32 v67, v33, v65
	v_lshlrev_b64 v[32:33], 11, v[172:173]
	v_mul_f32_e32 v68, v34, v65
	v_mul_f32_e32 v69, v35, v65
	v_lshl_add_u64 v[34:35], s[4:5], 0, v[32:33]
	v_lshl_add_u64 v[34:35], v[34:35], 0, s[6:7]
	v_mul_f32_e32 v48, v48, v65
	v_mul_f32_e32 v49, v49, v65
	v_mul_f32_e32 v50, v50, v65
	v_mul_f32_e32 v51, v51, v65
	v_mul_f32_e32 v70, v36, v65
	v_mul_f32_e32 v71, v37, v65
	v_mul_f32_e32 v72, v38, v65
	v_lshl_add_u64 v[34:35], v[34:35], 0, v[170:171]
	v_cvt_pk_bf16_f32 v232, v48, v49
	v_cvt_pk_bf16_f32 v233, v50, v51
	v_cvt_pk_bf16_f32 v240, v66, v67
	v_mul_f32_e32 v52, v52, v65
	v_mul_f32_e32 v53, v53, v65
	v_mul_f32_e32 v54, v54, v65
	v_mul_f32_e32 v55, v55, v65
	v_mul_f32_e32 v73, v39, v65
	v_mul_f32_e32 v40, v40, v65
	v_cvt_pk_bf16_f32 v241, v68, v69
	s_nop 0
	s_nop 0
	v_cvt_pk_bf16_f32 v234, v52, v53
	v_cvt_pk_bf16_f32 v235, v54, v55
	v_cvt_pk_bf16_f32 v242, v70, v71
	v_mul_f32_e32 v56, v56, v65
	v_mul_f32_e32 v57, v57, v65
	v_mul_f32_e32 v41, v41, v65
	v_mul_f32_e32 v58, v58, v65
	v_mul_f32_e32 v59, v59, v65
	v_cvt_pk_bf16_f32 v243, v72, v73
	v_and_b32_e32 v248, 32, v200
	v_lshrrev_b32_e32 v248, 2, v248
	v_mov_b32_e32 v249, 0
	v_lshl_add_u64 v[248:249], v[34:35], 0, v[248:249]
	v_permlane32_swap_b32_e32 v232, v234
	v_permlane32_swap_b32_e32 v233, v235
	global_store_dwordx4 v[248:249], v[232:235], off offset:1536
	s_nop 1
	v_permlane32_swap_b32_e32 v240, v242
	v_permlane32_swap_b32_e32 v241, v243
	global_store_dwordx4 v[248:249], v[240:243], off offset:1600
	v_cvt_pk_bf16_f32 v236, v56, v57
	v_cvt_pk_bf16_f32 v237, v58, v59
	v_cvt_pk_bf16_f32 v244, v40, v41
	ds_bpermute_b32 v40, v196, v64
	v_mul_f32_e32 v42, v42, v65
	v_mul_f32_e32 v43, v43, v65
	v_cvt_pk_bf16_f32 v245, v42, v43
	s_nop 0
	s_waitcnt lgkmcnt(0)
	v_add_f32_e32 v39, v64, v40
	v_max_f32_e32 v40, 0xda24260, v39
	v_div_scale_f32 v41, s[0:1], v40, v40, 1.0
	v_rcp_f32_e32 v42, v41
	v_mul_f32_e32 v60, v60, v65
	v_mul_f32_e32 v61, v61, v65
	v_mul_f32_e32 v62, v62, v65
	v_mul_f32_e32 v63, v63, v65
	s_nop 0
	v_cvt_pk_bf16_f32 v238, v60, v61
	v_cvt_pk_bf16_f32 v239, v62, v63
	v_mfma_f32_32x32x16_bf16 v[0:15], v[92:95], v[74:77], v[0:15]
	v_mul_f32_e32 v44, v44, v65
	v_mul_f32_e32 v45, v45, v65
	v_mul_f32_e32 v46, v46, v65
	v_mul_f32_e32 v47, v47, v65
	v_cvt_pk_bf16_f32 v246, v44, v45
	v_cvt_pk_bf16_f32 v247, v46, v47
	v_permlane32_swap_b32_e32 v236, v238
	v_permlane32_swap_b32_e32 v237, v239
	global_store_dwordx4 v[248:249], v[236:239], off offset:1568
	s_nop 1
	v_permlane32_swap_b32_e32 v244, v246
	v_permlane32_swap_b32_e32 v245, v247
	global_store_dwordx4 v[248:249], v[244:247], off offset:1632
	v_fma_f32 v34, -v41, v42, 1.0
	v_fmac_f32_e32 v42, v34, v42
	v_div_scale_f32 v34, vcc, 1.0, v40, 1.0
	v_mfma_f32_32x32x16_bf16 v[16:31], v[88:91], v[74:77], v[16:31]
	v_mul_f32_e32 v35, v34, v42
	v_fma_f32 v36, -v41, v35, v34
	v_fmac_f32_e32 v35, v36, v42
	v_fma_f32 v34, -v41, v35, v34
	v_div_fmas_f32 v34, v34, v42, v35
	v_div_fixup_f32 v34, v34, v40, 1.0
	v_or_b32_e32 v32, 0x10000, v32
	v_mul_f32_e32 v35, v0, v34
	v_mul_f32_e32 v36, v1, v34
	v_lshl_add_u64 v[0:1], s[4:5], 0, v[32:33]
	v_mul_f32_e32 v3, v3, v34
	v_lshl_add_u64 v[0:1], v[0:1], 0, s[6:7]
	v_mul_f32_e32 v16, v16, v34
	v_mul_f32_e32 v17, v17, v34
	v_mul_f32_e32 v37, v2, v34
	v_mul_f32_e32 v18, v18, v34
	v_mul_f32_e32 v19, v19, v34
	v_mul_f32_e32 v38, v4, v34
	v_mul_f32_e32 v39, v5, v34
	v_lshl_add_u64 v[0:1], v[0:1], 0, v[170:171]
	v_cvt_pk_bf16_f32 v232, v35, v36
	v_cvt_pk_bf16_f32 v233, v37, v3
	v_cvt_pk_bf16_f32 v240, v16, v17
	v_cvt_pk_bf16_f32 v241, v18, v19
	v_mul_f32_e32 v20, v20, v34
	v_mul_f32_e32 v21, v21, v34
	v_mul_f32_e32 v6, v6, v34
	v_mul_f32_e32 v22, v22, v34
	v_mul_f32_e32 v7, v7, v34
	v_mul_f32_e32 v23, v23, v34
	s_nop 0
	s_nop 0
	v_cvt_pk_bf16_f32 v234, v38, v39
	v_cvt_pk_bf16_f32 v235, v6, v7
	v_cvt_pk_bf16_f32 v242, v20, v21
	v_cvt_pk_bf16_f32 v243, v22, v23
	v_mul_f32_e32 v8, v8, v34
	v_mul_f32_e32 v24, v24, v34
	v_mul_f32_e32 v9, v9, v34
	v_mul_f32_e32 v25, v25, v34
	v_mul_f32_e32 v10, v10, v34
	v_mul_f32_e32 v26, v26, v34
	v_mul_f32_e32 v11, v11, v34
	v_mul_f32_e32 v27, v27, v34
	v_and_b32_e32 v248, 32, v200
	v_lshrrev_b32_e32 v248, 2, v248
	v_mov_b32_e32 v249, 0
	v_lshl_add_u64 v[248:249], v[0:1], 0, v[248:249]
	v_permlane32_swap_b32_e32 v232, v234
	v_permlane32_swap_b32_e32 v233, v235
	global_store_dwordx4 v[248:249], v[232:235], off offset:1536
	v_permlane32_swap_b32_e32 v240, v242
	v_permlane32_swap_b32_e32 v241, v243
	global_store_dwordx4 v[248:249], v[240:243], off offset:1600
	v_cvt_pk_bf16_f32 v236, v8, v9
	v_cvt_pk_bf16_f32 v237, v10, v11
	v_cvt_pk_bf16_f32 v244, v24, v25
	v_cvt_pk_bf16_f32 v245, v26, v27
	v_mul_f32_e32 v12, v12, v34
	v_mul_f32_e32 v28, v28, v34
	v_mul_f32_e32 v13, v13, v34
	v_mul_f32_e32 v29, v29, v34
	v_mul_f32_e32 v14, v14, v34
	v_mul_f32_e32 v30, v30, v34
	v_mul_f32_e32 v15, v15, v34
	v_mul_f32_e32 v31, v31, v34
	s_nop 0
	s_nop 0
	v_cvt_pk_bf16_f32 v238, v12, v13
	v_cvt_pk_bf16_f32 v239, v14, v15
	v_cvt_pk_bf16_f32 v246, v28, v29
	v_cvt_pk_bf16_f32 v247, v30, v31
	v_permlane32_swap_b32_e32 v236, v238
	v_permlane32_swap_b32_e32 v237, v239
	global_store_dwordx4 v[248:249], v[236:239], off offset:1568
	s_nop 1
	v_permlane32_swap_b32_e32 v244, v246
	v_permlane32_swap_b32_e32 v245, v247
	global_store_dwordx4 v[248:249], v[244:247], off offset:1632
	s_cbranch_scc0 .LBB0_1351
